# lazy LN-in: prologue input LayerNorm writes XB + row stats only; layer-0 out epilogue re-applies it to raw x_prompt/x_sample; single lazy epilogue for all layers
# baseline (speedup 1.0000x reference)
; DI void phase_prologue(const Params& p, char* smem) {
;     ...
;   {
;     const int stride = gridDim.x * NWAVES;
;     for (int row = blockIdx.x * NWAVES + (tid >> 6); row < MT; row += 2 * stride) {
;       const int row2 = row + stride;
;       const float* src = row < MP ? p.x_prompt + (size_t)row * 1024 : p.x_sample + (size_t)(row - MP) * 1024;
;       if (row2 < MT) {
;         const float* src2 = row2 < MP ? p.x_prompt + (size_t)row2 * 1024 : p.x_sample + (size_t)(row2 - MP) * 1024;
;         ln_rows2(src, src2, p.ln_in_g, p.ln_in_b, p.out + (size_t)row * 1024, (reinterpret_cast<bf16_t*>(p.ws + OFF_XB)) + (size_t)row * 1024, p.out + (size_t)row2 * 1024, (reinterpret_cast<bf16_t*>(p.ws + OFF_XB)) + (size_t)row2 * 1024, lane);
;       } else ln_row_wave(src, p.ln_in_g, p.ln_in_b, p.out + (size_t)row * 1024, (reinterpret_cast<bf16_t*>(p.ws + OFF_XB)) + (size_t)row * 1024, lane);
.LBB0_5:
	s_or_b64 exec, exec, s[2:3]
	s_load_dwordx16 s[8:23], s[0:1], 0x0
	v_ashrrev_i32_e32 v1, 6, v2
	s_waitcnt lgkmcnt(0)
	v_writelane_b32 v249, s8, 10
	s_nop 1
	v_writelane_b32 v249, s9, 11
	v_writelane_b32 v249, s10, 12
	v_writelane_b32 v249, s11, 13
	v_writelane_b32 v249, s12, 14
	v_writelane_b32 v249, s13, 15
	v_writelane_b32 v249, s14, 16
	v_writelane_b32 v249, s15, 17
	v_writelane_b32 v249, s16, 18
	v_writelane_b32 v249, s17, 19
	v_writelane_b32 v249, s18, 20
	v_writelane_b32 v249, s19, 21
	v_writelane_b32 v249, s20, 22
	v_writelane_b32 v249, s21, 23
	v_writelane_b32 v249, s22, 24
	v_writelane_b32 v249, s23, 25
	s_load_dwordx16 s[8:23], s[0:1], 0x40
	s_waitcnt lgkmcnt(0)
	v_writelane_b32 v249, s8, 26
	s_nop 1
	v_writelane_b32 v249, s9, 27
	v_writelane_b32 v249, s10, 28
	v_writelane_b32 v249, s11, 29
	v_writelane_b32 v249, s12, 30
	v_writelane_b32 v249, s13, 31
	v_writelane_b32 v249, s14, 32
	v_writelane_b32 v249, s15, 33
	v_writelane_b32 v249, s16, 34
	s_load_dword s0, s[4:5], 0x10
	v_writelane_b32 v249, s17, 35
	v_writelane_b32 v249, s18, 36
	v_writelane_b32 v249, s19, 37
	v_writelane_b32 v249, s20, 38
	v_writelane_b32 v249, s21, 39
	s_waitcnt lgkmcnt(0)
	s_lshr_b32 s0, s0, 16
	v_writelane_b32 v249, s22, 40
	s_cmp_lg_u32 s0, 0
	v_writelane_b32 v249, s23, 41
	s_cselect_b64 s[0:1], -1, 0
	s_cmp_lg_u64 s[0:1], 0
	v_readlane_b32 s0, v249, 6
	s_addc_u32 s24, s0, 0
	v_readlane_b32 s0, v249, 7
	s_lshl_b32 s0, s0, 3
	s_nop 0
	v_writelane_b32 v249, s0, 9
	v_add_u32_e32 v26, s0, v1
	s_mov_b32 s0, 0x10200
	v_cmp_gt_i32_e32 vcc, s0, v26
	s_and_saveexec_b64 s[0:1], vcc
	s_cbranch_execz .LBB0_16
	v_readlane_b32 s8, v249, 2
	s_lshl_b32 s15, s24, 3
	v_and_b32_e32 v2, 63, v2
	v_readlane_b32 s9, v249, 3
	v_mov_b32_e32 v29, 0
	v_lshlrev_b32_e32 v1, 3, v2
	v_readlane_b32 s8, v249, 0
	v_add_u32_e32 v38, s15, v26
	v_or_b32_e32 v10, 0x600, v1
	v_mov_b32_e32 v11, v29
	v_readlane_b32 s9, v249, 1
	v_readlane_b32 s36, v249, 10
	v_ashrrev_i32_e32 v39, 31, v38
	v_lshl_add_u64 v[32:33], s[8:9], 0, v[10:11]
	v_readlane_b32 s37, v249, 11
	v_lshlrev_b64 v[10:11], 12, v[38:39]
	v_ashrrev_i32_e32 v27, 31, v26
	v_lshlrev_b32_e32 v28, 4, v2
	v_lshl_add_u64 v[40:41], s[36:37], 0, v[10:11]
	v_lshlrev_b64 v[10:11], 12, v[26:27]
	v_readlane_b32 s10, v249, 4
	v_readlane_b32 s11, v249, 5
	v_or_b32_e32 v10, v10, v28
	v_readlane_b32 s40, v249, 14
	v_readlane_b32 s41, v249, 15
	v_readlane_b32 s42, v249, 16
	v_readlane_b32 s43, v249, 17
	v_readlane_b32 s44, v249, 18
	v_readlane_b32 s45, v249, 19
	v_readlane_b32 s46, v249, 20
	v_readlane_b32 s47, v249, 21
	v_readlane_b32 s48, v249, 22
	v_readlane_b32 s49, v249, 23
	v_readlane_b32 s50, v249, 24
	v_readlane_b32 s51, v249, 25
	v_lshl_add_u64 v[42:43], s[10:11], 0, v[10:11]
	v_lshlrev_b64 v[10:11], 11, v[26:27]
	v_lshlrev_b32_e32 v4, 2, v2
	s_lshl_b32 s2, s24, 4
	v_lshl_add_u64 v[34:35], s[50:51], 0, v[28:29]
	v_readlane_b32 s40, v249, 26
	v_or_b32_e32 v10, v10, v1
	v_or_b32_e32 v6, 0x100, v4
	v_or_b32_e32 v8, 0x200, v4
	v_readlane_b32 s38, v249, 12
	v_readlane_b32 s39, v249, 13
	v_readlane_b32 s41, v249, 27
	s_ashr_i32 s3, s2, 31
	v_lshl_add_u64 v[10:11], s[8:9], 0, v[10:11]
	s_mov_b64 s[8:9], 0x400
	v_lshl_add_u64 v[30:31], s[10:11], 0, v[28:29]
	v_lshl_add_u64 v[36:37], s[40:41], 0, v[28:29]
	s_lshl_b64 s[6:7], s[2:3], 12
	v_lshl_add_u64 v[44:45], v[10:11], 0, s[8:9]
	s_lshl_b64 s[8:9], s[2:3], 11
	v_lshlrev_b64 v[46:47], 10, v[26:27]
	s_lshl_b64 s[10:11], s[2:3], 10
	s_mov_b64 s[12:13], 0
	s_mov_b32 s25, 0x10000
	v_mov_b32_e32 v1, s39
	v_mov_b32_e32 v49, s37
	v_mov_b32_e32 v60, s38
	v_mov_b32_e32 v61, s36
	s_mov_b32 s26, 0x101ff
	s_mov_b32 s14, 0x3a800000
	v_mov_b32_e32 v48, 0x3727c5ac
	s_mov_b32 s27, 0x800000
	s_mov_b32 s28, 0xffff
	v_lshlrev_b32_e32 v50, 1, v4
	v_lshlrev_b32_e32 v52, 1, v6
	v_lshlrev_b32_e32 v54, 1, v8
	v_lshlrev_b32_e32 v28, 4, v2
	s_mov_b64 s[16:17], 0
	s_mov_b64 s[18:19], 0
	v_mov_b32_e32 v62, v26
	v_readlane_b32 s42, v249, 28
	v_readlane_b32 s43, v249, 29
	v_readlane_b32 s44, v249, 30
	v_readlane_b32 s45, v249, 31
	v_readlane_b32 s46, v249, 32
	v_readlane_b32 s47, v249, 33
	v_readlane_b32 s48, v249, 34
	v_readlane_b32 s49, v249, 35
	v_readlane_b32 s50, v249, 36
	v_readlane_b32 s51, v249, 37
	v_readlane_b32 s52, v249, 38
	v_readlane_b32 s53, v249, 39
	v_readlane_b32 s54, v249, 40
	v_readlane_b32 s55, v249, 41
	v_readlane_b32 s56, v249, 0
	v_readlane_b32 s57, v249, 1
	s_add_u32 s56, s56, 0x2b234000
	s_addc_u32 s57, s57, 0
	s_branch .LBB0_9
; DI float wave_sum(float x) { x = row_sum16(x); F2 a = swap16(x); x = a.lo + a.hi; F2 b = swap32(x); return b.lo + b.hi; }
; DI void ln_rows2(const float* s0, const float* s1, const float* g, const float* b, float* d0, bf16_t* db0, float* d1, bf16_t* db1, int lane) {
;   float4 v0[4], v1[4]; float a0 = 0.f, a1 = 0.f;
; #pragma unroll
;   for (int i = 0; i < 4; ++i) { v0[i] = reinterpret_cast<const float4*>(s0)[lane + 64 * i]; v1[i] = reinterpret_cast<const float4*>(s1)[lane + 64 * i]; }
; #pragma unroll
;   for (int i = 0; i < 4; ++i) { a0 += v0[i].x + v0[i].y + v0[i].z + v0[i].w; a1 += v1[i].x + v1[i].y + v1[i].z + v1[i].w; }
;   a0 = wave_sum(a0); a1 = wave_sum(a1);
;   const float mu0 = a0 * (1.f / 1024.f), mu1 = a1 * (1.f / 1024.f);
;   float q0 = 0.f, q1 = 0.f;
; #pragma unroll
;   for (int i = 0; i < 4; ++i) {
;     { float a = v0[i].x - mu0, bb = v0[i].y - mu0, c = v0[i].z - mu0, d = v0[i].w - mu0; q0 += a * a + bb * bb + c * c + d * d; }
;     { float a = v1[i].x - mu1, bb = v1[i].y - mu1, c = v1[i].z - mu1, d = v1[i].w - mu1; q1 += a * a + bb * bb + c * c + d * d; }
;   }
;   q0 = wave_sum(q0); q1 = wave_sum(q1);
;   const float r0 = rsqrtf(q0 * (1.f / 1024.f) + LN_EPS), r1 = rsqrtf(q1 * (1.f / 1024.f) + LN_EPS);
.LBB0_7:
	s_or_b64 exec, exec, s[22:23]
	v_lshl_add_u64 v[18:19], v[6:7], 0, v[28:29]
	v_lshl_add_u64 v[68:69], v[2:3], 0, v[28:29]
	global_load_dwordx4 v[2:5], v[68:69], off offset:3072
	global_load_dwordx4 v[6:9], v[18:19], off
	global_load_dwordx4 v[10:13], v[18:19], off offset:1024
	global_load_dwordx4 v[14:17], v[18:19], off offset:2048
	s_nop 0
	global_load_dwordx4 v[18:21], v[18:19], off offset:3072
	s_nop 0
	global_load_dwordx4 v[22:25], v[68:69], off
	global_load_dwordx4 v[64:67], v[68:69], off offset:1024
	s_nop 0
	global_load_dwordx4 v[68:71], v[68:69], off offset:2048
	s_nop 0
	global_load_dwordx4 v[72:75], v[34:35], off
	global_load_dwordx4 v[76:79], v[36:37], off
	v_readlane_b32 s22, v249, 0
	v_readlane_b32 s23, v249, 1
	s_waitcnt vmcnt(9)
	v_add_f32_e32 v51, v2, v3
	s_waitcnt vmcnt(8)
	v_add_f32_e32 v53, v6, v7
	s_waitcnt vmcnt(7)
	v_add_f32_e32 v55, v10, v11
	v_add_f32_e32 v53, v53, v8
	s_waitcnt vmcnt(6)
	v_add_f32_e32 v63, v14, v15
	v_add_f32_e32 v55, v55, v12
	v_add_f32_e32 v53, v53, v9
	s_waitcnt vmcnt(5)
	v_add_f32_e32 v80, v18, v19
	s_waitcnt vmcnt(4)
	v_add_f32_e32 v81, v22, v23
	v_add_f32_e32 v63, v63, v16
	v_add_f32_e32 v55, v55, v13
	v_add_f32_e32 v53, 0, v53
	s_waitcnt vmcnt(3)
	v_add_f32_e32 v82, v64, v65
	v_add_f32_e32 v81, v81, v24
	v_add_f32_e32 v80, v80, v20
	v_add_f32_e32 v63, v63, v17
	v_add_f32_e32 v53, v53, v55
	s_waitcnt vmcnt(2)
	v_add_f32_e32 v83, v68, v69
	v_add_f32_e32 v82, v82, v66
	v_add_f32_e32 v81, v81, v25
	v_add_f32_e32 v80, v80, v21
	v_add_f32_e32 v53, v53, v63
	v_add_f32_e32 v83, v83, v70
	v_add_f32_e32 v82, v82, v67
	v_add_f32_e32 v81, 0, v81
	v_add_f32_e32 v53, v53, v80
	v_add_f32_e32 v51, v51, v4
	v_add_f32_e32 v83, v83, v71
	v_add_f32_e32 v55, v81, v82
	v_add_f32_dpp v53, v53, v53 quad_perm:[1,0,3,2] row_mask:0xf bank_mask:0xf bound_ctrl:1
	v_add_f32_e32 v51, v51, v5
	v_add_f32_e32 v55, v55, v83
	v_add_f32_dpp v53, v53, v53 quad_perm:[2,3,0,1] row_mask:0xf bank_mask:0xf bound_ctrl:1
	v_add_f32_e32 v51, v55, v51
	s_nop 0
	v_add_f32_dpp v53, v53, v53 row_half_mirror row_mask:0xf bank_mask:0xf bound_ctrl:1
	v_add_f32_dpp v51, v51, v51 quad_perm:[1,0,3,2] row_mask:0xf bank_mask:0xf bound_ctrl:1
	s_nop 0
	v_add_f32_dpp v53, v53, v53 row_mirror row_mask:0xf bank_mask:0xf bound_ctrl:1
	v_add_f32_dpp v51, v51, v51 quad_perm:[2,3,0,1] row_mask:0xf bank_mask:0xf bound_ctrl:1
	v_mov_b32_e32 v55, v53
	s_nop 1
	v_permlane16_swap_b32_e32 v53, v55
	v_add_f32_dpp v51, v51, v51 row_half_mirror row_mask:0xf bank_mask:0xf bound_ctrl:1
	v_add_f32_e32 v53, v53, v55
	v_mov_b32_e32 v55, v53
	v_add_f32_dpp v51, v51, v51 row_mirror row_mask:0xf bank_mask:0xf bound_ctrl:1
	v_mov_b32_e32 v63, v51
	s_nop 1
	v_permlane16_swap_b32_e32 v51, v63
	v_permlane32_swap_b32_e32 v53, v55
	v_add_f32_e32 v51, v51, v63
	v_add_f32_e32 v53, v53, v55
	v_mov_b32_e32 v63, v51
	v_mul_f32_e32 v80, 0x3a800000, v53
	v_mov_b32_e32 v102, v80
	s_nop 0
	v_permlane32_swap_b32_e32 v51, v63
	v_pk_add_f32 v[6:7], v[6:7], v[80:81] op_sel_hi:[1,0] neg_lo:[0,1] neg_hi:[0,1]
	v_pk_add_f32 v[10:11], v[10:11], v[80:81] op_sel_hi:[1,0] neg_lo:[0,1] neg_hi:[0,1]
	v_add_f32_e32 v51, v51, v63
	v_pk_add_f32 v[8:9], v[8:9], v[80:81] op_sel_hi:[1,0] neg_lo:[0,1] neg_hi:[0,1]
	v_pk_add_f32 v[12:13], v[12:13], v[80:81] op_sel_hi:[1,0] neg_lo:[0,1] neg_hi:[0,1]
	v_pk_add_f32 v[14:15], v[14:15], v[80:81] op_sel_hi:[1,0] neg_lo:[0,1] neg_hi:[0,1]
	v_pk_add_f32 v[16:17], v[16:17], v[80:81] op_sel_hi:[1,0] neg_lo:[0,1] neg_hi:[0,1]
	v_pk_add_f32 v[18:19], v[18:19], v[80:81] op_sel_hi:[1,0] neg_lo:[0,1] neg_hi:[0,1]
	v_pk_add_f32 v[20:21], v[20:21], v[80:81] op_sel_hi:[1,0] neg_lo:[0,1] neg_hi:[0,1]
	v_pk_mul_f32 v[80:81], v[6:7], v[6:7]
	v_pk_mul_f32 v[84:85], v[10:11], v[10:11]
	v_mul_f32_e32 v82, 0x3a800000, v51
	v_mov_b32_e32 v104, v82
	v_pk_mul_f32 v[86:87], v[12:13], v[12:13]
	v_pk_mul_f32 v[88:89], v[8:9], v[8:9]
	v_pk_mul_f32 v[90:91], v[14:15], v[14:15]
	v_add_f32_e32 v51, v84, v85
	v_add_f32_e32 v53, v80, v81
	v_pk_mul_f32 v[92:93], v[16:17], v[16:17]
	v_pk_mul_f32 v[94:95], v[18:19], v[18:19]
	v_add_f32_e32 v55, v90, v91
	v_add_f32_e32 v51, v86, v51
	v_add_f32_e32 v53, v88, v53
	v_pk_mul_f32 v[96:97], v[20:21], v[20:21]
	v_add_f32_e32 v63, v94, v95
	v_add_f32_e32 v55, v92, v55
	v_add_f32_e32 v51, v87, v51
	v_add_f32_e32 v53, v89, v53
	v_add_f32_e32 v63, v96, v63
	v_add_f32_e32 v55, v93, v55
	v_add_f32_e32 v51, v53, v51
	v_add_f32_e32 v63, v97, v63
	v_add_f32_e32 v51, v55, v51
	v_pk_add_f32 v[80:81], v[2:3], v[82:83] op_sel_hi:[1,0] neg_lo:[0,1] neg_hi:[0,1]
	v_add_f32_e32 v2, v63, v51
	v_pk_add_f32 v[64:65], v[64:65], v[82:83] op_sel_hi:[1,0] neg_lo:[0,1] neg_hi:[0,1]
	v_pk_add_f32 v[22:23], v[22:23], v[82:83] op_sel_hi:[1,0] neg_lo:[0,1] neg_hi:[0,1]
	v_add_f32_dpp v2, v2, v2 quad_perm:[1,0,3,2] row_mask:0xf bank_mask:0xf bound_ctrl:1
	v_pk_add_f32 v[24:25], v[24:25], v[82:83] op_sel_hi:[1,0] neg_lo:[0,1] neg_hi:[0,1]
	v_pk_add_f32 v[66:67], v[66:67], v[82:83] op_sel_hi:[1,0] neg_lo:[0,1] neg_hi:[0,1]
	v_add_f32_dpp v2, v2, v2 quad_perm:[2,3,0,1] row_mask:0xf bank_mask:0xf bound_ctrl:1
	v_pk_add_f32 v[68:69], v[68:69], v[82:83] op_sel_hi:[1,0] neg_lo:[0,1] neg_hi:[0,1]
	v_pk_add_f32 v[70:71], v[70:71], v[82:83] op_sel_hi:[1,0] neg_lo:[0,1] neg_hi:[0,1]
	v_add_f32_dpp v2, v2, v2 row_half_mirror row_mask:0xf bank_mask:0xf bound_ctrl:1
	v_pk_add_f32 v[82:83], v[4:5], v[82:83] op_sel_hi:[1,0] neg_lo:[0,1] neg_hi:[0,1]
	v_pk_mul_f32 v[4:5], v[64:65], v[64:65]
	v_add_f32_dpp v2, v2, v2 row_mirror row_mask:0xf bank_mask:0xf bound_ctrl:1
	v_mov_b32_e32 v3, v2
	s_nop 1
	v_permlane16_swap_b32_e32 v2, v3
	v_add_f32_e32 v3, v2, v3
	v_add_f32_e32 v2, v4, v5
; DI bf16x4 pack4(float a, float b, float c, float d) { u32x2v u; u.x = pk2(a, b); u.y = pk2(c, d); return __builtin_bit_cast(bf16x4, u); }
; DI float wave_sum(float x) { x = row_sum16(x); F2 a = swap16(x); x = a.lo + a.hi; F2 b = swap32(x); return b.lo + b.hi; }
; DI void ln_rows2(const float* s0, const float* s1, const float* g, const float* b, float* d0, bf16_t* db0, float* d1, bf16_t* db1, int lane) {
;     ...
;   q0 = wave_sum(q0); q1 = wave_sum(q1);
;   const float r0 = rsqrtf(q0 * (1.f / 1024.f) + LN_EPS), r1 = rsqrtf(q1 * (1.f / 1024.f) + LN_EPS);
; #pragma unroll
;   for (int i = 0; i < 4; ++i) {
;     const float4 gg = reinterpret_cast<const float4*>(g)[lane + 64 * i], bb = reinterpret_cast<const float4*>(b)[lane + 64 * i];
;     float4 o;
;     o.x = (v0[i].x - mu0) * r0 * gg.x + bb.x; o.y = (v0[i].y - mu0) * r0 * gg.y + bb.y; o.z = (v0[i].z - mu0) * r0 * gg.z + bb.z; o.w = (v0[i].w - mu0) * r0 * gg.w + bb.w;
;     reinterpret_cast<float4*>(d0)[lane + 64 * i] = o; st4(db0 + 4 * (lane + 64 * i), pack4(o.x, o.y, o.z, o.w));
;     o.x = (v1[i].x - mu1) * r1 * gg.x + bb.x; o.y = (v1[i].y - mu1) * r1 * gg.y + bb.y; o.z = (v1[i].z - mu1) * r1 * gg.z + bb.z; o.w = (v1[i].w - mu1) * r1 * gg.w + bb.w;
;     reinterpret_cast<float4*>(d1)[lane + 64 * i] = o; st4(db1 + 4 * (lane + 64 * i), pack4(o.x, o.y, o.z, o.w));
;   }
; }
	v_pk_mul_f32 v[4:5], v[22:23], v[22:23]
	v_pk_mul_f32 v[84:85], v[66:67], v[66:67]
	v_add_f32_e32 v51, v4, v5
	v_pk_mul_f32 v[4:5], v[24:25], v[24:25]
	v_add_f32_e32 v2, v84, v2
	v_add_f32_e32 v4, v4, v51
	v_add_f32_e32 v2, v85, v2
	v_add_f32_e32 v51, v5, v4
	v_pk_mul_f32 v[4:5], v[68:69], v[68:69]
	v_add_f32_e32 v2, v51, v2
	v_add_f32_e32 v51, v4, v5
	v_pk_mul_f32 v[4:5], v[70:71], v[70:71]
	v_mov_b32_e32 v53, v29
	v_add_f32_e32 v4, v4, v51
	v_add_f32_e32 v51, v5, v4
	v_pk_mul_f32 v[4:5], v[80:81], v[80:81]
	v_add_f32_e32 v2, v51, v2
	v_add_f32_e32 v51, v4, v5
	v_pk_mul_f32 v[4:5], v[82:83], v[82:83]
	v_mov_b32_e32 v55, v29
	v_add_f32_e32 v4, v4, v51
	v_add_f32_e32 v4, v5, v4
	v_add_f32_e32 v2, v4, v2
	v_mov_b32_e32 v5, v3
	s_nop 1
	v_permlane32_swap_b32_e32 v3, v5
	v_add_f32_dpp v2, v2, v2 quad_perm:[1,0,3,2] row_mask:0xf bank_mask:0xf bound_ctrl:1
	s_nop 1
	v_add_f32_dpp v2, v2, v2 quad_perm:[2,3,0,1] row_mask:0xf bank_mask:0xf bound_ctrl:1
	s_nop 1
	v_add_f32_dpp v2, v2, v2 row_half_mirror row_mask:0xf bank_mask:0xf bound_ctrl:1
	s_nop 1
	v_add_f32_dpp v2, v2, v2 row_mirror row_mask:0xf bank_mask:0xf bound_ctrl:1
	v_mov_b32_e32 v4, v2
	s_nop 1
	v_permlane16_swap_b32_e32 v2, v4
	v_add_f32_e32 v2, v2, v4
	v_mov_b32_e32 v4, v2
	s_nop 1
	v_permlane32_swap_b32_e32 v2, v4
	v_pk_add_f32 v[2:3], v[2:3], v[4:5]
	s_nop 0
	v_pk_fma_f32 v[2:3], v[2:3], s[14:15], v[48:49] op_sel_hi:[1,0,0]
	s_nop 0
	v_mul_f32_e32 v4, 0x4b800000, v3
	v_cmp_gt_f32_e32 vcc, s27, v3
	s_nop 1
	v_cndmask_b32_e32 v3, v3, v4, vcc
	v_rsq_f32_e32 v3, v3
	s_nop 0
	v_mul_f32_e32 v4, 0x45800000, v3
	v_cndmask_b32_e32 v84, v3, v4, vcc
	v_mul_f32_e32 v3, 0x4b800000, v2
	v_cmp_gt_f32_e32 vcc, s27, v2
	v_pk_mul_f32 v[4:5], v[6:7], v[84:85] op_sel_hi:[1,0]
	v_pk_mul_f32 v[6:7], v[8:9], v[84:85] op_sel_hi:[1,0]
	v_cndmask_b32_e32 v2, v2, v3, vcc
	v_rsq_f32_e32 v51, v2
	s_waitcnt vmcnt(0)
	v_pk_fma_f32 v[2:3], v[72:73], v[4:5], v[76:77]
	v_pk_fma_f32 v[4:5], v[74:75], v[6:7], v[78:79]
	v_mul_f32_e32 v6, 0x45800000, v51
	v_cndmask_b32_e32 v86, v51, v6, vcc
	v_pk_mul_f32 v[6:7], v[22:23], v[86:87] op_sel_hi:[1,0]
	v_pk_mul_f32 v[8:9], v[24:25], v[86:87] op_sel_hi:[1,0]
	v_cvt_pk_bf16_f32 v22, v2, v3
	v_lshlrev_b64 v[2:3], 11, v[58:59]
	v_pk_fma_f32 v[6:7], v[72:73], v[6:7], v[76:77]
	v_pk_fma_f32 v[8:9], v[74:75], v[8:9], v[78:79]
	v_lshl_add_u64 v[24:25], s[22:23], 0, v[2:3]
	v_lshlrev_b64 v[2:3], 12, v[58:59]
	v_mov_b32_e32 v51, v29
	v_cvt_pk_bf16_f32 v23, v4, v5
	v_lshl_add_u64 v[72:73], v[30:31], 0, v[2:3]
	v_cvt_pk_bf16_f32 v2, v6, v7
	v_cvt_pk_bf16_f32 v3, v8, v9
	v_lshl_add_u64 v[4:5], v[24:25], 0, v[50:51]
	global_store_dwordx2 v[44:45], v[22:23], off offset:-1024
	global_store_dwordx2 v[4:5], v[2:3], off
	global_load_dwordx4 v[2:5], v[34:35], off offset:1024
	s_nop 0
	global_load_dwordx4 v[6:9], v[36:37], off offset:1024
	v_pk_mul_f32 v[10:11], v[10:11], v[84:85] op_sel_hi:[1,0]
	v_pk_mul_f32 v[12:13], v[12:13], v[84:85] op_sel_hi:[1,0]
	v_pk_mul_f32 v[64:65], v[64:65], v[86:87] op_sel_hi:[1,0]
	v_pk_mul_f32 v[66:67], v[66:67], v[86:87] op_sel_hi:[1,0]
	v_lshl_add_u64 v[22:23], v[24:25], 0, v[52:53]
	s_waitcnt vmcnt(0)
	v_pk_fma_f32 v[10:11], v[10:11], v[2:3], v[6:7]
	v_pk_fma_f32 v[12:13], v[12:13], v[4:5], v[8:9]
	v_pk_fma_f32 v[2:3], v[64:65], v[2:3], v[6:7]
	v_pk_fma_f32 v[4:5], v[66:67], v[4:5], v[8:9]
	v_cvt_pk_bf16_f32 v6, v10, v11
	v_cvt_pk_bf16_f32 v7, v12, v13
	v_cvt_pk_bf16_f32 v8, v2, v3
	v_cvt_pk_bf16_f32 v9, v4, v5
	global_store_dwordx2 v[44:45], v[6:7], off offset:-512
	global_store_dwordx2 v[22:23], v[8:9], off
	global_load_dwordx4 v[2:5], v[34:35], off offset:2048
	s_nop 0
	global_load_dwordx4 v[6:9], v[36:37], off offset:2048
	v_pk_mul_f32 v[10:11], v[14:15], v[84:85] op_sel_hi:[1,0]
	v_pk_mul_f32 v[12:13], v[16:17], v[84:85] op_sel_hi:[1,0]
	v_pk_mul_f32 v[14:15], v[68:69], v[86:87] op_sel_hi:[1,0]
	v_pk_mul_f32 v[16:17], v[70:71], v[86:87] op_sel_hi:[1,0]
	v_lshl_add_u64 v[22:23], v[24:25], 0, v[54:55]
	s_waitcnt vmcnt(0)
	v_pk_fma_f32 v[10:11], v[10:11], v[2:3], v[6:7]
	v_pk_fma_f32 v[12:13], v[12:13], v[4:5], v[8:9]
	v_pk_fma_f32 v[2:3], v[14:15], v[2:3], v[6:7]
	v_pk_fma_f32 v[4:5], v[16:17], v[4:5], v[8:9]
	v_cvt_pk_bf16_f32 v6, v10, v11
	v_cvt_pk_bf16_f32 v7, v12, v13
	v_cvt_pk_bf16_f32 v8, v2, v3
	v_cvt_pk_bf16_f32 v9, v4, v5
	global_store_dwordx2 v[44:45], v[6:7], off
	global_store_dwordx2 v[22:23], v[8:9], off
	global_load_dwordx4 v[2:5], v[34:35], off offset:3072
	s_nop 0
	global_load_dwordx4 v[10:13], v[36:37], off offset:3072
	v_pk_mul_f32 v[6:7], v[18:19], v[84:85] op_sel_hi:[1,0]
	v_pk_mul_f32 v[16:17], v[20:21], v[84:85] op_sel_hi:[1,0]
	v_pk_mul_f32 v[18:19], v[80:81], v[86:87] op_sel_hi:[1,0]
	v_pk_mul_f32 v[20:21], v[82:83], v[86:87] op_sel_hi:[1,0]
	v_lshlrev_b64 v[8:9], 10, v[58:59]
	s_waitcnt vmcnt(0)
	v_pk_fma_f32 v[14:15], v[6:7], v[2:3], v[10:11]
	v_pk_fma_f32 v[16:17], v[16:17], v[4:5], v[12:13]
	v_pk_fma_f32 v[2:3], v[18:19], v[2:3], v[10:11]
	v_cvt_pk_bf16_f32 v6, v14, v15
	v_cvt_pk_bf16_f32 v7, v16, v17
	v_pk_fma_f32 v[4:5], v[20:21], v[4:5], v[12:13]
	global_store_dwordx2 v[44:45], v[6:7], off offset:512
	v_mov_b32_e32 v103, v84
	v_mov_b32_e32 v105, v86
	v_lshlrev_b32_e32 v106, 3, v62
	v_lshlrev_b32_e32 v107, 3, v58
	global_store_dwordx2 v106, v[102:103], s[56:57]
	global_store_dwordx2 v107, v[104:105], s[56:57]
.LBB0_8:
	s_or_b64 exec, exec, s[20:21]
	s_add_u32 s18, s18, s6
	s_addc_u32 s19, s19, s7
	v_add_u32_e32 v62, s2, v62
	s_add_u32 s16, s16, s2
	v_lshl_add_u64 v[6:7], v[8:9], 2, v[30:31]
	s_addc_u32 s17, s17, s3
	v_cmp_lt_i32_e32 vcc, s26, v62
	v_lshl_add_u64 v[6:7], v[8:9], 1, v[32:33]
	v_lshl_add_u64 v[44:45], v[44:45], 0, s[8:9]
	v_cvt_pk_bf16_f32 v2, v2, v3
	v_cvt_pk_bf16_f32 v3, v4, v5
	s_or_b64 s[12:13], vcc, s[12:13]
	v_lshl_add_u64 v[46:47], v[46:47], 0, s[10:11]
	global_store_dwordx2 v[6:7], v[2:3], off
	s_andn2_b64 exec, exec, s[12:13]
	s_cbranch_execz .LBB0_16
; DI bf16x4 pack4(float a, float b, float c, float d) { u32x2v u; u.x = pk2(a, b); u.y = pk2(c, d); return __builtin_bit_cast(bf16x4, u); }
; DI float wave_sum(float x) { x = row_sum16(x); F2 a = swap16(x); x = a.lo + a.hi; F2 b = swap32(x); return b.lo + b.hi; }
; DI void ln_row_wave(const float* src, const float* g, const float* b, float* d32, bf16_t* db, int lane) {
;   float4 v[4]; float s = 0.f;
; #pragma unroll
;   for (int i = 0; i < 4; ++i) { v[i] = reinterpret_cast<const float4*>(src)[lane + 64 * i]; s += v[i].x + v[i].y + v[i].z + v[i].w; }
;   s = wave_sum(s);
;   const float mu = s * (1.f / 1024.f);
;   float q = 0.f;
; #pragma unroll
;   for (int i = 0; i < 4; ++i) { float a = v[i].x - mu, bb = v[i].y - mu, c = v[i].z - mu, d = v[i].w - mu; q += a * a + bb * bb + c * c + d * d; }
;   q = wave_sum(q);
;   const float rstd = rsqrtf(q * (1.f / 1024.f) + LN_EPS);
; #pragma unroll
;   for (int i = 0; i < 4; ++i) {
;     float4 gg = reinterpret_cast<const float4*>(g)[lane + 64 * i], bb = reinterpret_cast<const float4*>(b)[lane + 64 * i];
;     float4 o;
;     o.x = (v[i].x - mu) * rstd * gg.x + bb.x; o.y = (v[i].y - mu) * rstd * gg.y + bb.y;
;     o.z = (v[i].z - mu) * rstd * gg.z + bb.z; o.w = (v[i].w - mu) * rstd * gg.w + bb.w;
;     reinterpret_cast<float4*>(d32)[lane + 64 * i] = o;
;     st4(db + 4 * (lane + 64 * i), pack4(o.x, o.y, o.z, o.w));
;   }
; DI void phase_prologue(const Params& p, char* smem) {
;     ...
;     for (int row = blockIdx.x * NWAVES + (tid >> 6); row < MT; row += 2 * stride) {
;       const int row2 = row + stride;
;       const float* src = row < MP ? p.x_prompt + (size_t)row * 1024 : p.x_sample + (size_t)(row - MP) * 1024;
;       if (row2 < MT) {
;         const float* src2 = row2 < MP ? p.x_prompt + (size_t)row2 * 1024 : p.x_sample + (size_t)(row2 - MP) * 1024;
;         ln_rows2(src, src2, p.ln_in_g, p.ln_in_b, p.out + (size_t)row * 1024, (reinterpret_cast<bf16_t*>(p.ws + OFF_XB)) + (size_t)row * 1024, p.out + (size_t)row2 * 1024, (reinterpret_cast<bf16_t*>(p.ws + OFF_XB)) + (size_t)row2 * 1024, lane);
;       } else ln_row_wave(src, p.ln_in_g, p.ln_in_b, p.out + (size_t)row * 1024, (reinterpret_cast<bf16_t*>(p.ws + OFF_XB)) + (size_t)row * 1024, lane);
.LBB0_9:
	v_add_u32_e32 v4, 0xffff0000, v62
	v_lshl_add_u64 v[2:3], v[26:27], 0, s[16:17]
	v_cmp_gt_i32_e32 vcc, s25, v62
	v_add_u32_e32 v58, s15, v62
	v_lshl_add_u64 v[56:57], v[42:43], 0, s[18:19]
	v_cndmask_b32_e32 v3, 0, v3, vcc
	v_cndmask_b32_e32 v2, v4, v2, vcc
	v_cndmask_b32_e32 v5, v1, v49, vcc
	v_cndmask_b32_e32 v4, v60, v61, vcc
	v_lshlrev_b64 v[2:3], 12, v[2:3]
	v_lshl_add_u64 v[6:7], v[4:5], 0, v[2:3]
	v_cmp_lt_i32_e32 vcc, s26, v58
	s_and_saveexec_b64 s[20:21], vcc
	s_xor_b64 s[20:21], exec, s[20:21]
	s_cbranch_execz .LBB0_11
	v_lshl_add_u64 v[14:15], v[6:7], 0, v[28:29]
	global_load_dwordx4 v[2:5], v[14:15], off offset:3072
	global_load_dwordx4 v[6:9], v[14:15], off
	global_load_dwordx4 v[10:13], v[14:15], off offset:1024
	s_nop 0
	global_load_dwordx4 v[14:17], v[14:15], off offset:2048
	s_nop 0
	global_load_dwordx4 v[18:21], v[34:35], off
	global_load_dwordx4 v[22:25], v[36:37], off
	s_waitcnt vmcnt(5)
	v_add_f32_e32 v51, v2, v3
	s_waitcnt vmcnt(4)
	v_add_f32_e32 v53, v6, v7
	s_waitcnt vmcnt(3)
	v_add_f32_e32 v55, v10, v11
	v_add_f32_e32 v53, v53, v8
	s_waitcnt vmcnt(2)
	v_add_f32_e32 v58, v14, v15
	v_add_f32_e32 v55, v55, v12
	v_add_f32_e32 v53, v53, v9
	v_add_f32_e32 v58, v58, v16
	v_add_f32_e32 v55, v55, v13
	v_add_f32_e32 v53, 0, v53
	v_add_f32_e32 v51, v51, v4
	v_add_f32_e32 v58, v58, v17
	v_add_f32_e32 v53, v53, v55
	v_add_f32_e32 v51, v51, v5
	v_add_f32_e32 v53, v53, v58
	v_add_f32_e32 v51, v53, v51
	s_nop 1
	v_add_f32_dpp v51, v51, v51 quad_perm:[1,0,3,2] row_mask:0xf bank_mask:0xf bound_ctrl:1
	s_nop 1
	v_add_f32_dpp v51, v51, v51 quad_perm:[2,3,0,1] row_mask:0xf bank_mask:0xf bound_ctrl:1
	s_nop 1
	v_add_f32_dpp v51, v51, v51 row_half_mirror row_mask:0xf bank_mask:0xf bound_ctrl:1
	s_nop 1
	v_add_f32_dpp v51, v51, v51 row_mirror row_mask:0xf bank_mask:0xf bound_ctrl:1
	v_mov_b32_e32 v53, v51
	s_nop 1
	v_permlane16_swap_b32_e32 v51, v53
	v_add_f32_e32 v51, v51, v53
	v_mov_b32_e32 v53, v51
	s_nop 1
	v_permlane32_swap_b32_e32 v51, v53
	v_add_f32_e32 v51, v51, v53
	v_mul_f32_e32 v58, 0x3a800000, v51
	v_mov_b32_e32 v102, v58
	v_pk_add_f32 v[6:7], v[6:7], v[58:59] op_sel_hi:[1,0] neg_lo:[0,1] neg_hi:[0,1]
	v_pk_add_f32 v[10:11], v[10:11], v[58:59] op_sel_hi:[1,0] neg_lo:[0,1] neg_hi:[0,1]
	v_pk_add_f32 v[8:9], v[8:9], v[58:59] op_sel_hi:[1,0] neg_lo:[0,1] neg_hi:[0,1]
	v_pk_add_f32 v[12:13], v[12:13], v[58:59] op_sel_hi:[1,0] neg_lo:[0,1] neg_hi:[0,1]
	v_pk_add_f32 v[14:15], v[14:15], v[58:59] op_sel_hi:[1,0] neg_lo:[0,1] neg_hi:[0,1]
	v_pk_add_f32 v[64:65], v[2:3], v[58:59] op_sel_hi:[1,0] neg_lo:[0,1] neg_hi:[0,1]
	v_pk_mul_f32 v[2:3], v[6:7], v[6:7]
	v_pk_mul_f32 v[66:67], v[10:11], v[10:11]
	v_pk_add_f32 v[16:17], v[16:17], v[58:59] op_sel_hi:[1,0] neg_lo:[0,1] neg_hi:[0,1]
	v_pk_add_f32 v[58:59], v[4:5], v[58:59] op_sel_hi:[1,0] neg_lo:[0,1] neg_hi:[0,1]
	v_pk_mul_f32 v[4:5], v[8:9], v[8:9]
	v_pk_mul_f32 v[68:69], v[12:13], v[12:13]
	v_pk_mul_f32 v[70:71], v[14:15], v[14:15]
	v_add_f32_e32 v51, v66, v67
	v_add_f32_e32 v2, v2, v3
	v_pk_mul_f32 v[72:73], v[16:17], v[16:17]
	v_pk_mul_f32 v[74:75], v[64:65], v[64:65]
	v_add_f32_e32 v3, v70, v71
	v_add_f32_e32 v51, v68, v51
	v_add_f32_e32 v2, v4, v2
	v_pk_mul_f32 v[76:77], v[58:59], v[58:59]
	v_add_f32_e32 v53, v74, v75
	v_add_f32_e32 v3, v72, v3
	v_add_f32_e32 v51, v69, v51
	v_add_f32_e32 v2, v5, v2
	v_add_f32_e32 v4, v76, v53
	v_add_f32_e32 v3, v73, v3
	v_add_f32_e32 v2, v2, v51
	v_add_f32_e32 v4, v77, v4
	v_add_f32_e32 v2, v3, v2
	v_add_f32_e32 v2, v4, v2
	s_nop 1
	v_add_f32_dpp v2, v2, v2 quad_perm:[1,0,3,2] row_mask:0xf bank_mask:0xf bound_ctrl:1
	s_nop 1
	v_add_f32_dpp v2, v2, v2 quad_perm:[2,3,0,1] row_mask:0xf bank_mask:0xf bound_ctrl:1
	s_nop 1
	v_add_f32_dpp v2, v2, v2 row_half_mirror row_mask:0xf bank_mask:0xf bound_ctrl:1
	s_nop 1
	v_add_f32_dpp v2, v2, v2 row_mirror row_mask:0xf bank_mask:0xf bound_ctrl:1
	v_mov_b32_e32 v3, v2
	s_nop 1
	v_permlane16_swap_b32_e32 v2, v3
	v_add_f32_e32 v2, v2, v3
	v_mov_b32_e32 v3, v2
	s_nop 1
	v_permlane32_swap_b32_e32 v2, v3
	v_add_f32_e32 v2, v2, v3
	v_fmamk_f32 v2, v2, 0x3a800000, v48
	v_mul_f32_e32 v3, 0x4b800000, v2
	v_cmp_gt_f32_e32 vcc, s27, v2
	s_nop 1
	v_cndmask_b32_e32 v2, v2, v3, vcc
	v_rsq_f32_e32 v2, v2
	s_nop 0
	v_mul_f32_e32 v3, 0x45800000, v2
	v_cndmask_b32_e32 v66, v2, v3, vcc
	v_pk_mul_f32 v[2:3], v[6:7], v[66:67] op_sel_hi:[1,0]
	v_pk_mul_f32 v[4:5], v[8:9], v[66:67] op_sel_hi:[1,0]
	s_waitcnt vmcnt(0)
	v_pk_fma_f32 v[2:3], v[18:19], v[2:3], v[22:23]
	v_pk_fma_f32 v[4:5], v[20:21], v[4:5], v[24:25]
	v_pk_mul_f32 v[10:11], v[10:11], v[66:67] op_sel_hi:[1,0]
	v_pk_mul_f32 v[12:13], v[12:13], v[66:67] op_sel_hi:[1,0]
	v_cvt_pk_bf16_f32 v2, v2, v3
	v_cvt_pk_bf16_f32 v3, v4, v5
	global_store_dwordx2 v[44:45], v[2:3], off offset:-1024
	global_load_dwordx4 v[2:5], v[34:35], off offset:1024
	s_nop 0
	global_load_dwordx4 v[6:9], v[36:37], off offset:1024
	s_waitcnt vmcnt(0)
	v_pk_fma_f32 v[2:3], v[10:11], v[2:3], v[6:7]
	v_pk_fma_f32 v[4:5], v[12:13], v[4:5], v[8:9]
	v_pk_mul_f32 v[10:11], v[14:15], v[66:67] op_sel_hi:[1,0]
	v_pk_mul_f32 v[12:13], v[16:17], v[66:67] op_sel_hi:[1,0]
	v_cvt_pk_bf16_f32 v2, v2, v3
	v_cvt_pk_bf16_f32 v3, v4, v5
	global_store_dwordx2 v[44:45], v[2:3], off offset:-512
	global_load_dwordx4 v[2:5], v[34:35], off offset:2048
	s_nop 0
	global_load_dwordx4 v[6:9], v[36:37], off offset:2048
	s_waitcnt vmcnt(0)
	v_pk_fma_f32 v[2:3], v[10:11], v[2:3], v[6:7]
	v_pk_fma_f32 v[4:5], v[12:13], v[4:5], v[8:9]
	v_pk_mul_f32 v[10:11], v[64:65], v[66:67] op_sel_hi:[1,0]
	v_pk_mul_f32 v[12:13], v[58:59], v[66:67] op_sel_hi:[1,0]
	v_cvt_pk_bf16_f32 v2, v2, v3
	v_cvt_pk_bf16_f32 v3, v4, v5
	global_store_dwordx2 v[44:45], v[2:3], off
	global_load_dwordx4 v[2:5], v[34:35], off offset:3072
	s_nop 0
	global_load_dwordx4 v[6:9], v[36:37], off offset:3072
	s_waitcnt vmcnt(0)
	v_pk_fma_f32 v[2:3], v[10:11], v[2:3], v[6:7]
	v_pk_fma_f32 v[4:5], v[12:13], v[4:5], v[8:9]
	v_mov_b32_e32 v103, v66
	v_lshlrev_b32_e32 v106, 3, v62
	global_store_dwordx2 v106, v[102:103], s[56:57]

; #define PG8_STAGE(bufoff, gbase, voff) do { _Pragma("unroll") for (int _i = 0; _i < 2; ++_i) \
;         __builtin_amdgcn_global_load_lds((const unsigned*)((const char*)(gbase) + (voff)[_i]), (PG8_LAS unsigned*)(lds + (bufoff) + ldsw + _i * 8192), 16, 0, 0); } while (0)
; #define PG8_LDA(dst, b, h) do { _Pragma("unroll") for (int m = 0; m < 4; ++m) _Pragma("unroll") for (int k = 0; k < 2; ++k) dst[m][k] = *(const PG8_LAS bf16x8*)(lds + PG8_SA(b, h) + aoff + m * 2048 + k * 1024); } while (0)
; #define PG8_LDB(dst, b, h) do { _Pragma("unroll") for (int n = 0; n < 2; ++n) _Pragma("unroll") for (int k = 0; k < 2; ++k) dst[n][k] = *(const PG8_LAS bf16x8*)(lds + PG8_SB(b, h) + boff + n * 2048 + k * 1024); } while (0)
; #define PG8_MMA(ai, bj, At, Bt) do { __builtin_amdgcn_s_setprio(1); _Pragma("unroll") for (int m = 0; m < 4; ++m) _Pragma("unroll") for (int n = 0; n < 2; ++n) _Pragma("unroll") for (int k = 0; k < 2; ++k) \
;         acc[ai][bj][m][n] = __builtin_amdgcn_mfma_f32_16x16x32_bf16(Bt[n][k], At[m][k], acc[ai][bj][m][n], 0, 0, 0); __builtin_amdgcn_s_setprio(0); } while (0)
; #define PG8_WAIT_V(n) asm volatile("s_waitcnt vmcnt(" #n ")" ::: "memory")
; #define PG8_WAIT_L(n) asm volatile("s_waitcnt lgkmcnt(" #n ")" ::: "memory")
; #define PG8_BAR __builtin_amdgcn_s_barrier()
; #define PG8_SCHED __builtin_amdgcn_sched_barrier(0)
; template <class Epi, class Sched>
; __device__ __forceinline__ void gemm_phase(PG8_LAS unsigned char* lds, const Gemm g, const Sched& S, const Epi& E) {
;     ...
;             PG8_LDB(B0, 0, 0); PG8_SCHED; PG8_LDA(At, 0, 0); PG8_STAGE(PG8_SA(1, 1), a1 + hstep, voffA);
;             PG8_WAIT_L(8); PG8_BAR; PG8_WAIT_L(0); PG8_MMA(0, 0, At, B0); PG8_BAR; PG8_SCHED;
;             PG8_LDB(B1, 0, 1); PG8_STAGE(PG8_SB(0, 0), b2, voffB);
;             PG8_BAR; PG8_WAIT_L(0); PG8_MMA(0, 1, At, B1); PG8_BAR;
;             PG8_LDA(At, 0, 1); PG8_STAGE(PG8_SA(0, 0), a2, voffA);
;             PG8_BAR; PG8_WAIT_L(0); PG8_MMA(1, 0, At, B0); PG8_BAR; PG8_SCHED;
;             PG8_STAGE(PG8_SB(0, 1), b2 + hstep, voffB);
;             PG8_WAIT_V(6); PG8_BAR; PG8_MMA(1, 1, At, B1); PG8_BAR;
.LBB0_2754:
	s_add_u32 s14, s12, 0xfffc0080
	s_addc_u32 s15, s13, -1
	s_add_i32 s37, 0, 0x10000
	v_add_u32_e32 v140, s37, v142
	ds_read_b128 v[144:147], v140
	ds_read_b128 v[148:151], v140 offset:1024
	ds_read_b128 v[162:165], v140 offset:2048
	ds_read_b128 v[166:169], v140 offset:3072
	s_cmp_eq_u32 s36, 12
	s_cselect_b32 s17, s5, s15
	s_cselect_b32 s16, s31, s14
	s_cselect_b32 s15, s3, s35
	s_cselect_b32 s14, s33, s34
	v_lshl_add_u64 v[140:141], s[12:13], 0, v[136:137]
	s_add_i32 m0, s23, 0xc000
	ds_read_b128 v[170:173], v143
	ds_read_b128 v[174:177], v143 offset:1024
	ds_read_b128 v[178:181], v143 offset:2048
	ds_read_b128 v[188:191], v143 offset:3072
	ds_read_b128 v[192:195], v143 offset:4096
	ds_read_b128 v[196:199], v143 offset:5120
	ds_read_b128 v[200:203], v143 offset:6144
	ds_read_b128 v[204:207], v143 offset:7168
	global_load_lds_dwordx4 v[140:141], off
	v_lshl_add_u64 v[140:141], s[12:13], 0, v[138:139]
	s_add_i32 m0, s23, 0xe000
	s_nop 0
	global_load_lds_dwordx4 v[140:141], off
	s_waitcnt lgkmcnt(8)
	s_barrier
	s_waitcnt lgkmcnt(0)
	s_setprio 1
	s_waitcnt lgkmcnt(0)
	v_mfma_f32_16x16x32_bf16 v[130:133], v[144:147], v[170:173], v[130:133]
	v_mfma_f32_16x16x32_bf16 v[126:129], v[162:165], v[170:173], v[126:129]
	v_mfma_f32_16x16x32_bf16 v[114:117], v[144:147], v[178:181], v[114:117]
	v_mfma_f32_16x16x32_bf16 v[110:113], v[162:165], v[178:181], v[110:113]
	v_mfma_f32_16x16x32_bf16 v[98:101], v[144:147], v[192:195], v[98:101]
	v_mfma_f32_16x16x32_bf16 v[94:97], v[162:165], v[192:195], v[94:97]
	v_mfma_f32_16x16x32_bf16 v[82:85], v[144:147], v[200:203], v[82:85]
	v_mfma_f32_16x16x32_bf16 v[78:81], v[162:165], v[200:203], v[78:81]
	v_mfma_f32_16x16x32_bf16 v[130:133], v[148:151], v[174:177], v[130:133]
	v_mfma_f32_16x16x32_bf16 v[126:129], v[166:169], v[174:177], v[126:129]
	v_mfma_f32_16x16x32_bf16 v[114:117], v[148:151], v[188:191], v[114:117]
	v_mfma_f32_16x16x32_bf16 v[110:113], v[166:169], v[188:191], v[110:113]
	v_mfma_f32_16x16x32_bf16 v[98:101], v[148:151], v[196:199], v[98:101]
	v_mfma_f32_16x16x32_bf16 v[94:97], v[166:169], v[196:199], v[94:97]
	v_mfma_f32_16x16x32_bf16 v[82:85], v[148:151], v[204:207], v[82:85]
	v_mfma_f32_16x16x32_bf16 v[78:81], v[166:169], v[204:207], v[78:81]
	s_setprio 0
	s_barrier
	s_add_i32 s40, 0, 0x14000
	v_add_u32_e32 v140, s40, v142
	s_add_i32 s37, s37, s21
	ds_read_b128 v[208:211], v140
	ds_read_b128 v[212:215], v140 offset:1024
	ds_read_b128 v[216:219], v140 offset:2048
	ds_read_b128 v[220:223], v140 offset:3072
	v_lshl_add_u64 v[140:141], s[14:15], 0, v[134:135]
	s_mov_b32 m0, s37
	v_lshl_add_u64 v[154:155], s[14:15], 0, v[18:19]
	global_load_lds_dwordx4 v[140:141], off
	s_add_i32 m0, s37, 0x2000
	s_nop 0
	global_load_lds_dwordx4 v[154:155], off
	s_barrier
	s_waitcnt lgkmcnt(0)
	s_setprio 1
	s_waitcnt lgkmcnt(0)
	v_mfma_f32_16x16x32_bf16 v[122:125], v[208:211], v[170:173], v[122:125]
	v_mfma_f32_16x16x32_bf16 v[118:121], v[216:219], v[170:173], v[118:121]
	v_mfma_f32_16x16x32_bf16 v[106:109], v[208:211], v[178:181], v[106:109]
	v_mfma_f32_16x16x32_bf16 v[102:105], v[216:219], v[178:181], v[102:105]
	v_mfma_f32_16x16x32_bf16 v[90:93], v[208:211], v[192:195], v[90:93]
	v_mfma_f32_16x16x32_bf16 v[86:89], v[216:219], v[192:195], v[86:89]
	v_mfma_f32_16x16x32_bf16 v[74:77], v[208:211], v[200:203], v[74:77]
	v_mfma_f32_16x16x32_bf16 v[70:73], v[216:219], v[200:203], v[70:73]
	v_mfma_f32_16x16x32_bf16 v[122:125], v[212:215], v[174:177], v[122:125]
	v_mfma_f32_16x16x32_bf16 v[118:121], v[220:223], v[174:177], v[118:121]
	v_mfma_f32_16x16x32_bf16 v[106:109], v[212:215], v[188:191], v[106:109]
	v_mfma_f32_16x16x32_bf16 v[102:105], v[220:223], v[188:191], v[102:105]
	v_mfma_f32_16x16x32_bf16 v[90:93], v[212:215], v[196:199], v[90:93]
	v_mfma_f32_16x16x32_bf16 v[86:89], v[220:223], v[196:199], v[86:89]
	v_mfma_f32_16x16x32_bf16 v[74:77], v[212:215], v[204:207], v[74:77]
	v_mfma_f32_16x16x32_bf16 v[70:73], v[220:223], v[204:207], v[70:73]
	s_setprio 0
	s_mov_b32 m0, s23
	v_lshl_add_u64 v[156:157], s[16:17], 0, v[134:135]
	s_barrier
	ds_read_b128 v[170:173], v143 offset:16384
	ds_read_b128 v[174:177], v143 offset:17408
	ds_read_b128 v[178:181], v143 offset:18432
	ds_read_b128 v[188:191], v143 offset:19456
	ds_read_b128 v[192:195], v143 offset:20480
	ds_read_b128 v[196:199], v143 offset:21504
	ds_read_b128 v[200:203], v143 offset:22528
	ds_read_b128 v[204:207], v143 offset:23552
	global_load_lds_dwordx4 v[156:157], off
	v_lshl_add_u64 v[186:187], s[16:17], 0, v[18:19]
	s_mov_b32 m0, s24
	s_nop 0
	global_load_lds_dwordx4 v[186:187], off
	s_barrier
	s_waitcnt lgkmcnt(0)
	s_setprio 1
	s_waitcnt lgkmcnt(0)
	v_mfma_f32_16x16x32_bf16 v[66:69], v[144:147], v[170:173], v[66:69]
	v_mfma_f32_16x16x32_bf16 v[62:65], v[162:165], v[170:173], v[62:65]
	v_mfma_f32_16x16x32_bf16 v[50:53], v[144:147], v[178:181], v[50:53]
	v_mfma_f32_16x16x32_bf16 v[46:49], v[162:165], v[178:181], v[46:49]
	v_mfma_f32_16x16x32_bf16 v[34:37], v[144:147], v[192:195], v[34:37]
	v_mfma_f32_16x16x32_bf16 v[30:33], v[162:165], v[192:195], v[30:33]
	v_mfma_f32_16x16x32_bf16 v[12:15], v[144:147], v[200:203], v[12:15]
	v_mfma_f32_16x16x32_bf16 v[8:11], v[162:165], v[200:203], v[8:11]
	v_mfma_f32_16x16x32_bf16 v[66:69], v[148:151], v[174:177], v[66:69]
	v_mfma_f32_16x16x32_bf16 v[62:65], v[166:169], v[174:177], v[62:65]
	v_mfma_f32_16x16x32_bf16 v[50:53], v[148:151], v[188:191], v[50:53]
	v_mfma_f32_16x16x32_bf16 v[46:49], v[166:169], v[188:191], v[46:49]
	v_mfma_f32_16x16x32_bf16 v[34:37], v[148:151], v[196:199], v[34:37]
	v_mfma_f32_16x16x32_bf16 v[30:33], v[166:169], v[196:199], v[30:33]
	v_mfma_f32_16x16x32_bf16 v[12:15], v[148:151], v[204:207], v[12:15]
	v_mfma_f32_16x16x32_bf16 v[8:11], v[166:169], v[204:207], v[8:11]
	s_setprio 0
	s_barrier
; #define PG8_STAGE(bufoff, gbase, voff) do { _Pragma("unroll") for (int _i = 0; _i < 2; ++_i) \
;         __builtin_amdgcn_global_load_lds((const unsigned*)((const char*)(gbase) + (voff)[_i]), (PG8_LAS unsigned*)(lds + (bufoff) + ldsw + _i * 8192), 16, 0, 0); } while (0)
; #define PG8_LDA(dst, b, h) do { _Pragma("unroll") for (int m = 0; m < 4; ++m) _Pragma("unroll") for (int k = 0; k < 2; ++k) dst[m][k] = *(const PG8_LAS bf16x8*)(lds + PG8_SA(b, h) + aoff + m * 2048 + k * 1024); } while (0)
; #define PG8_LDB(dst, b, h) do { _Pragma("unroll") for (int n = 0; n < 2; ++n) _Pragma("unroll") for (int k = 0; k < 2; ++k) dst[n][k] = *(const PG8_LAS bf16x8*)(lds + PG8_SB(b, h) + boff + n * 2048 + k * 1024); } while (0)
; #define PG8_MMA(ai, bj, At, Bt) do { __builtin_amdgcn_s_setprio(1); _Pragma("unroll") for (int m = 0; m < 4; ++m) _Pragma("unroll") for (int n = 0; n < 2; ++n) _Pragma("unroll") for (int k = 0; k < 2; ++k) \
;         acc[ai][bj][m][n] = __builtin_amdgcn_mfma_f32_16x16x32_bf16(Bt[n][k], At[m][k], acc[ai][bj][m][n], 0, 0, 0); __builtin_amdgcn_s_setprio(0); } while (0)
; #define PG8_WAIT_V(n) asm volatile("s_waitcnt vmcnt(" #n ")" ::: "memory")
; #define PG8_WAIT_L(n) asm volatile("s_waitcnt lgkmcnt(" #n ")" ::: "memory")
; #define PG8_BAR __builtin_amdgcn_s_barrier()
; #define PG8_SCHED __builtin_amdgcn_sched_barrier(0)
; template <class Epi, class Sched>
; __device__ __forceinline__ void gemm_phase(PG8_LAS unsigned char* lds, const Gemm g, const Sched& S, const Epi& E) {
;     ...
;             PG8_WAIT_V(6); PG8_BAR; PG8_MMA(1, 1, At, B1); PG8_BAR;
;             PG8_LDB(B0, 1, 0); PG8_SCHED; PG8_LDA(At, 1, 0); PG8_STAGE(PG8_SA(0, 1), a2 + hstep, voffA);
;             PG8_WAIT_L(8); PG8_BAR; PG8_WAIT_L(0); PG8_MMA(0, 0, At, B0); PG8_BAR; PG8_SCHED;
;             PG8_LDB(B1, 1, 1); PG8_STAGE(PG8_SB(1, 0), b3, voffB);
;             PG8_BAR; PG8_WAIT_L(0); PG8_MMA(0, 1, At, B1); PG8_BAR;
;             PG8_LDA(At, 1, 1); PG8_STAGE(PG8_SA(1, 0), a3, voffA);
;             PG8_BAR; PG8_WAIT_L(0); PG8_MMA(1, 0, At, B0); PG8_BAR; PG8_SCHED;
	s_add_u32 s38, s14, 0x40000
	s_addc_u32 s39, s15, 0
	s_add_i32 s37, s40, s21
	v_lshl_add_u64 v[144:145], s[38:39], 0, v[134:135]
	s_mov_b32 m0, s37
	s_nop 0
	global_load_lds_dwordx4 v[144:145], off
	v_lshl_add_u64 v[144:145], s[38:39], 0, v[18:19]
	s_add_i32 m0, s37, 0x2000
	s_nop 0
	global_load_lds_dwordx4 v[144:145], off
	s_waitcnt vmcnt(6)
	s_barrier
	s_setprio 1
	v_mfma_f32_16x16x32_bf16 v[58:61], v[208:211], v[170:173], v[58:61]
	v_mfma_f32_16x16x32_bf16 v[54:57], v[216:219], v[170:173], v[54:57]
	v_mfma_f32_16x16x32_bf16 v[42:45], v[208:211], v[178:181], v[42:45]
	v_mfma_f32_16x16x32_bf16 v[38:41], v[216:219], v[178:181], v[38:41]
	v_mfma_f32_16x16x32_bf16 v[26:29], v[208:211], v[192:195], v[26:29]
	v_mfma_f32_16x16x32_bf16 v[22:25], v[216:219], v[192:195], v[22:25]
	v_mfma_f32_16x16x32_bf16 v[4:7], v[208:211], v[200:203], v[4:7]
	v_mfma_f32_16x16x32_bf16 v[0:3], v[216:219], v[200:203], v[0:3]
	v_mfma_f32_16x16x32_bf16 v[58:61], v[212:215], v[174:177], v[58:61]
	v_mfma_f32_16x16x32_bf16 v[54:57], v[220:223], v[174:177], v[54:57]
	v_mfma_f32_16x16x32_bf16 v[42:45], v[212:215], v[188:191], v[42:45]
	v_mfma_f32_16x16x32_bf16 v[38:41], v[220:223], v[188:191], v[38:41]
	v_mfma_f32_16x16x32_bf16 v[26:29], v[212:215], v[196:199], v[26:29]
	v_mfma_f32_16x16x32_bf16 v[22:25], v[220:223], v[196:199], v[22:25]
	v_mfma_f32_16x16x32_bf16 v[4:7], v[212:215], v[204:207], v[4:7]
	v_mfma_f32_16x16x32_bf16 v[0:3], v[220:223], v[204:207], v[0:3]
	s_setprio 0
	s_add_i32 s37, 0, 0x18000
	v_add_u32_e32 v166, s37, v142
	s_barrier
	ds_read_b128 v[144:147], v166
	ds_read_b128 v[148:151], v166 offset:1024
	ds_read_b128 v[162:165], v166 offset:2048
	ds_read_b128 v[166:169], v166 offset:3072
	s_add_u32 s16, s16, 0x40000
	s_addc_u32 s17, s17, 0
	s_mov_b32 m0, s25
	v_lshl_add_u64 v[208:209], s[16:17], 0, v[134:135]
	ds_read_b128 v[170:173], v143 offset:32768
	ds_read_b128 v[174:177], v143 offset:33792
	ds_read_b128 v[178:181], v143 offset:34816
	ds_read_b128 v[188:191], v143 offset:35840
	ds_read_b128 v[192:195], v143 offset:36864
	ds_read_b128 v[196:199], v143 offset:37888
	ds_read_b128 v[200:203], v143 offset:38912
	ds_read_b128 v[204:207], v143 offset:39936
	global_load_lds_dwordx4 v[208:209], off
	v_lshl_add_u64 v[208:209], s[16:17], 0, v[18:19]
	s_mov_b32 m0, s26
	s_nop 0
	global_load_lds_dwordx4 v[208:209], off
	s_waitcnt lgkmcnt(8)
	s_barrier
	s_waitcnt lgkmcnt(0)
	s_setprio 1
	s_waitcnt lgkmcnt(0)
	v_mfma_f32_16x16x32_bf16 v[130:133], v[144:147], v[170:173], v[130:133]
	v_mfma_f32_16x16x32_bf16 v[126:129], v[162:165], v[170:173], v[126:129]
	v_mfma_f32_16x16x32_bf16 v[114:117], v[144:147], v[178:181], v[114:117]
	v_mfma_f32_16x16x32_bf16 v[110:113], v[162:165], v[178:181], v[110:113]
	v_mfma_f32_16x16x32_bf16 v[98:101], v[144:147], v[192:195], v[98:101]
	v_mfma_f32_16x16x32_bf16 v[94:97], v[162:165], v[192:195], v[94:97]
	v_mfma_f32_16x16x32_bf16 v[82:85], v[144:147], v[200:203], v[82:85]
	v_mfma_f32_16x16x32_bf16 v[78:81], v[162:165], v[200:203], v[78:81]
	v_mfma_f32_16x16x32_bf16 v[130:133], v[148:151], v[174:177], v[130:133]
	v_mfma_f32_16x16x32_bf16 v[126:129], v[166:169], v[174:177], v[126:129]
	v_mfma_f32_16x16x32_bf16 v[114:117], v[148:151], v[188:191], v[114:117]
	v_mfma_f32_16x16x32_bf16 v[110:113], v[166:169], v[188:191], v[110:113]
	v_mfma_f32_16x16x32_bf16 v[98:101], v[148:151], v[196:199], v[98:101]
	v_mfma_f32_16x16x32_bf16 v[94:97], v[166:169], v[196:199], v[94:97]
	v_mfma_f32_16x16x32_bf16 v[82:85], v[148:151], v[204:207], v[82:85]
	v_mfma_f32_16x16x32_bf16 v[78:81], v[166:169], v[204:207], v[78:81]
	s_setprio 0
	s_barrier
	s_add_i32 s16, 0, 0x1c000
	s_add_i32 s17, s37, s21
	v_add_u32_e32 v220, s16, v142
	v_lshl_add_u64 v[140:141], v[140:141], 0, s[42:43]
	s_mov_b32 m0, s17
	ds_read_b128 v[208:211], v220
	ds_read_b128 v[212:215], v220 offset:1024
	ds_read_b128 v[216:219], v220 offset:2048
	ds_read_b128 v[220:223], v220 offset:3072
	global_load_lds_dwordx4 v[140:141], off
	v_lshl_add_u64 v[140:141], v[154:155], 0, s[42:43]
	s_add_i32 m0, s17, 0x2000
	s_nop 0
	global_load_lds_dwordx4 v[140:141], off
	s_barrier
	s_waitcnt lgkmcnt(0)
	s_setprio 1
	s_waitcnt lgkmcnt(0)
	v_mfma_f32_16x16x32_bf16 v[122:125], v[208:211], v[170:173], v[122:125]
	v_mfma_f32_16x16x32_bf16 v[118:121], v[216:219], v[170:173], v[118:121]
	v_mfma_f32_16x16x32_bf16 v[106:109], v[208:211], v[178:181], v[106:109]
	v_mfma_f32_16x16x32_bf16 v[102:105], v[216:219], v[178:181], v[102:105]
	v_mfma_f32_16x16x32_bf16 v[90:93], v[208:211], v[192:195], v[90:93]
	v_mfma_f32_16x16x32_bf16 v[86:89], v[216:219], v[192:195], v[86:89]
	v_mfma_f32_16x16x32_bf16 v[74:77], v[208:211], v[200:203], v[74:77]
	v_mfma_f32_16x16x32_bf16 v[70:73], v[216:219], v[200:203], v[70:73]
	v_mfma_f32_16x16x32_bf16 v[122:125], v[212:215], v[174:177], v[122:125]
	v_mfma_f32_16x16x32_bf16 v[118:121], v[220:223], v[174:177], v[118:121]
	v_mfma_f32_16x16x32_bf16 v[106:109], v[212:215], v[188:191], v[106:109]
	v_mfma_f32_16x16x32_bf16 v[102:105], v[220:223], v[188:191], v[102:105]
	v_mfma_f32_16x16x32_bf16 v[90:93], v[212:215], v[196:199], v[90:93]
	v_mfma_f32_16x16x32_bf16 v[86:89], v[220:223], v[196:199], v[86:89]
	v_mfma_f32_16x16x32_bf16 v[74:77], v[212:215], v[204:207], v[74:77]
	v_mfma_f32_16x16x32_bf16 v[70:73], v[220:223], v[204:207], v[70:73]
	s_setprio 0
	s_mov_b32 m0, s27
	v_lshl_add_u64 v[140:141], v[156:157], 0, s[42:43]
	s_barrier
	ds_read_b128 v[170:173], v143 offset:49152
	ds_read_b128 v[174:177], v143 offset:50176
	ds_read_b128 v[178:181], v143 offset:51200
	ds_read_b128 v[188:191], v143 offset:52224
	ds_read_b128 v[192:195], v143 offset:53248
	ds_read_b128 v[196:199], v143 offset:54272
	ds_read_b128 v[200:203], v143 offset:55296
	ds_read_b128 v[204:207], v143 offset:56320
	global_load_lds_dwordx4 v[140:141], off
	v_lshl_add_u64 v[140:141], v[186:187], 0, s[42:43]
	s_mov_b32 m0, s28
	s_nop 0
	global_load_lds_dwordx4 v[140:141], off
	s_barrier
; DI bf16x4 pack4(float a, float b, float c, float d) { u32x2v u; u.x = pk2(a, b); u.y = pk2(c, d); return __builtin_bit_cast(bf16x4, u); }
; #define PG8_WAIT_V(n) asm volatile("s_waitcnt vmcnt(" #n ")" ::: "memory")
; #define PG8_WAIT_L(n) asm volatile("s_waitcnt lgkmcnt(" #n ")" ::: "memory")
; template <class Epi, class Sched>
; __device__ __forceinline__ void gemm_phase(PG8_LAS unsigned char* lds, const Gemm g, const Sched& S, const Epi& E) {
;     ...
;             PG8_WAIT_V(6); PG8_BAR; PG8_MMA(1, 1, At, B1); PG8_BAR;
;             PG8_LDB(B0, 1, 0); PG8_SCHED; PG8_LDA(At, 1, 0); PG8_STAGE(PG8_SA(0, 1), a2 + hstep, voffA);
;             PG8_WAIT_L(8); PG8_BAR; PG8_WAIT_L(0); PG8_MMA(0, 0, At, B0); PG8_BAR; PG8_SCHED;
;             PG8_LDB(B1, 1, 1); PG8_STAGE(PG8_SB(1, 0), b3, voffB);
;             PG8_BAR; PG8_WAIT_L(0); PG8_MMA(0, 1, At, B1); PG8_BAR;
;             PG8_LDA(At, 1, 1); PG8_STAGE(PG8_SA(1, 0), a3, voffA);
;             PG8_BAR; PG8_WAIT_L(0); PG8_MMA(1, 0, At, B0); PG8_BAR; PG8_SCHED;
;             PG8_STAGE(PG8_SB(1, 1), b3 + hstep, voffB);
;             PG8_WAIT_V(6); PG8_BAR; PG8_MMA(1, 1, At, B1); PG8_BAR;
;   DI void operator()(const f32x4 (&acc)[2][2][4][2], const pg8::Unit& u, int wr, int wc, int fr, int fq) const {
;     bf16_t* MERGED = (reinterpret_cast<bf16_t*>(p.ws + OFF_GA));
; #pragma unroll
;     for (int ai = 0; ai < 2; ++ai)
; #pragma unroll
;       for (int m = 0; m < 4; ++m) {
;         const int row = u.pm * 256 + 128 * ai + 64 * wr + 16 * m + fr;
; #pragma unroll
;         for (int bj = 0; bj < 2; ++bj)
; #pragma unroll
;           for (int n = 0; n < 2; ++n) {
;             const size_t idx = (size_t)row * 1024 + u.pn * 256 + 128 * bj + 32 * wc + 16 * n + 4 * fq;
;             const f32x4 a = acc[ai][bj][m][n];
;             if (MODE == 0) {
;               const unsigned g = *reinterpret_cast<const unsigned*>(reinterpret_cast<const unsigned char*>(p.ws + OFF_RB) + idx);
;               const float k = 1.f / 255.f;
;               st4(MERGED + idx, pack4((float)(g & 255u) * k * a[0], (float)((g >> 8) & 255u) * k * a[1], (float)((g >> 16) & 255u) * k * a[2], (float)(g >> 24) * k * a[3]));
;             } else {
;               f32x4 x = *reinterpret_cast<const f32x4*>(p.out + idx);
;               x = x * ALPHA + a;
;               *reinterpret_cast<f32x4*>(p.out + idx) = x;
;             }
;           }
;       }
	s_waitcnt lgkmcnt(0)
	s_setprio 1
	s_waitcnt lgkmcnt(0)
	v_mfma_f32_16x16x32_bf16 v[66:69], v[144:147], v[170:173], v[66:69]
	v_mfma_f32_16x16x32_bf16 v[62:65], v[162:165], v[170:173], v[62:65]
	v_mfma_f32_16x16x32_bf16 v[50:53], v[144:147], v[178:181], v[50:53]
	v_mfma_f32_16x16x32_bf16 v[46:49], v[162:165], v[178:181], v[46:49]
	v_mfma_f32_16x16x32_bf16 v[34:37], v[144:147], v[192:195], v[34:37]
	v_mfma_f32_16x16x32_bf16 v[30:33], v[162:165], v[192:195], v[30:33]
	v_mfma_f32_16x16x32_bf16 v[12:15], v[144:147], v[200:203], v[12:15]
	v_mfma_f32_16x16x32_bf16 v[8:11], v[162:165], v[200:203], v[8:11]
	v_mfma_f32_16x16x32_bf16 v[66:69], v[148:151], v[174:177], v[66:69]
	v_mfma_f32_16x16x32_bf16 v[62:65], v[166:169], v[174:177], v[62:65]
	v_mfma_f32_16x16x32_bf16 v[50:53], v[148:151], v[188:191], v[50:53]
	v_mfma_f32_16x16x32_bf16 v[46:49], v[166:169], v[188:191], v[46:49]
	v_mfma_f32_16x16x32_bf16 v[34:37], v[148:151], v[196:199], v[34:37]
	v_mfma_f32_16x16x32_bf16 v[30:33], v[166:169], v[196:199], v[30:33]
	v_mfma_f32_16x16x32_bf16 v[12:15], v[148:151], v[204:207], v[12:15]
	v_mfma_f32_16x16x32_bf16 v[8:11], v[166:169], v[204:207], v[8:11]
	s_setprio 0
	s_barrier
	s_add_u32 s14, s14, 0x40080
	s_addc_u32 s15, s15, 0
	s_add_i32 s16, s16, s21
	v_lshl_add_u64 v[140:141], s[14:15], 0, v[134:135]
	s_mov_b32 m0, s16
	s_nop 0
	global_load_lds_dwordx4 v[140:141], off
	v_lshl_add_u64 v[140:141], s[14:15], 0, v[18:19]
	s_add_i32 m0, s16, 0x2000
	s_nop 0
	global_load_lds_dwordx4 v[140:141], off
	s_waitcnt vmcnt(6)
	s_barrier
	s_setprio 1
	v_mfma_f32_16x16x32_bf16 v[58:61], v[208:211], v[170:173], v[58:61]
	v_mfma_f32_16x16x32_bf16 v[54:57], v[216:219], v[170:173], v[54:57]
	v_mfma_f32_16x16x32_bf16 v[42:45], v[208:211], v[178:181], v[42:45]
	v_mfma_f32_16x16x32_bf16 v[38:41], v[216:219], v[178:181], v[38:41]
	v_mfma_f32_16x16x32_bf16 v[26:29], v[208:211], v[192:195], v[26:29]
	v_mfma_f32_16x16x32_bf16 v[22:25], v[216:219], v[192:195], v[22:25]
	v_mfma_f32_16x16x32_bf16 v[4:7], v[208:211], v[200:203], v[4:7]
	v_mfma_f32_16x16x32_bf16 v[0:3], v[216:219], v[200:203], v[0:3]
	v_mfma_f32_16x16x32_bf16 v[58:61], v[212:215], v[174:177], v[58:61]
	v_mfma_f32_16x16x32_bf16 v[54:57], v[220:223], v[174:177], v[54:57]
	v_mfma_f32_16x16x32_bf16 v[42:45], v[212:215], v[188:191], v[42:45]
	v_mfma_f32_16x16x32_bf16 v[38:41], v[220:223], v[188:191], v[38:41]
	v_mfma_f32_16x16x32_bf16 v[26:29], v[212:215], v[196:199], v[26:29]
	v_mfma_f32_16x16x32_bf16 v[22:25], v[220:223], v[196:199], v[22:25]
	v_mfma_f32_16x16x32_bf16 v[4:7], v[212:215], v[204:207], v[4:7]
	v_mfma_f32_16x16x32_bf16 v[0:3], v[220:223], v[204:207], v[0:3]
	s_setprio 0
	s_add_i32 s36, s36, 2
	s_add_u32 s12, s12, 0x100
	s_addc_u32 s13, s13, 0
	s_add_u32 s34, s34, 0x100
	s_addc_u32 s35, s35, 0
	s_cmp_gt_u32 s36, 13
	s_barrier
	s_cbranch_scc0 .LBB0_2754
	v_readlane_b32 s12, v251, 8
	v_lshl_add_u32 v140, s10, 8, v21
	s_lshr_b32 s96, s10, 8
	s_lshl_b32 s10, s11, 10
	v_readlane_b32 s14, v249, 4
	v_readlane_b32 s15, v249, 5
	v_readlane_b32 s13, v251, 6
	s_mov_b32 s16, 0x3fd744fd
	v_lshlrev_b32_e32 v141, 3, v140
	s_add_i32 s10, s10, s13
	v_readlane_b32 s76, v249, 0
	v_readlane_b32 s77, v249, 1
	v_add_u32_e32 v144, s10, v16
	s_add_u32 s76, s76, 0x2b234000
	s_addc_u32 s77, s77, 0
	v_lshl_add_u32 v140, v140, 12, v144
	s_cmp_eq_u32 s12, 0
	s_cbranch_scc1 .Llz_l0
	s_add_i32 s12, s12, -1
	s_lshl_b32 s12, s12, 12
	v_readlane_b32 s72, v249, 38
	v_readlane_b32 s73, v249, 39
	v_readlane_b32 s74, v249, 40
	v_readlane_b32 s75, v249, 41
	s_mov_b64 s[94:95], s[14:15]
	s_add_u32 s72, s72, s12
	s_addc_u32 s73, s73, 0
	s_add_u32 s74, s74, s12
	s_addc_u32 s75, s75, 0
	s_branch .Llz_bases
.Llz_l0:
	v_readlane_b32 s72, v249, 24
	v_readlane_b32 s73, v249, 25
	v_readlane_b32 s74, v249, 26
	v_readlane_b32 s75, v249, 27
	v_readlane_b32 s94, v249, 10
	v_readlane_b32 s95, v249, 11
	s_cmp_eq_u32 s96, 0
	s_cbranch_scc1 .Llz_l0p
	v_readlane_b32 s94, v249, 12
	v_readlane_b32 s95, v249, 13
	s_nop 0
	s_sub_u32 s94, s94, 0x10000000
	s_subb_u32 s95, s95, 0
.Llz_l0p:
	s_add_u32 s72, s72, 0
	s_addc_u32 s73, s73, 0
	s_add_u32 s74, s74, 0
	s_addc_u32 s75, s75, 0
.Llz_bases:
	s_add_u32 s56, s14, 0x0
	s_addc_u32 s57, s15, 0
	s_add_u32 s78, s94, 0x0
	s_addc_u32 s79, s95, 0
	s_add_u32 s58, s14, 0x10000
	s_addc_u32 s59, s15, 0
	s_add_u32 s80, s94, 0x10000
	s_addc_u32 s81, s95, 0
	s_add_u32 s60, s14, 0x20000
	s_addc_u32 s61, s15, 0
	s_add_u32 s82, s94, 0x20000
	s_addc_u32 s83, s95, 0
	s_add_u32 s62, s14, 0x30000
	s_addc_u32 s63, s15, 0
	s_add_u32 s84, s94, 0x30000
	s_addc_u32 s85, s95, 0
	s_add_u32 s64, s14, 0x80000
	s_addc_u32 s65, s15, 0
	s_add_u32 s86, s94, 0x80000
	s_addc_u32 s87, s95, 0
	s_add_u32 s66, s14, 0x90000
	s_addc_u32 s67, s15, 0
	s_add_u32 s88, s94, 0x90000
	s_addc_u32 s89, s95, 0
	s_add_u32 s68, s14, 0xa0000
	s_addc_u32 s69, s15, 0
	s_add_u32 s90, s94, 0xa0000
	s_addc_u32 s91, s95, 0
	s_add_u32 s70, s14, 0xb0000
	s_addc_u32 s71, s15, 0
	s_add_u32 s92, s94, 0xb0000
	s_addc_u32 s93, s95, 0
	s_nop 1
	global_load_dwordx2 v[146:147], v141, s[76:77] offset:0
	global_load_dwordx2 v[148:149], v141, s[76:77] offset:128
	global_load_dwordx2 v[150:151], v141, s[76:77] offset:256
	global_load_dwordx2 v[154:155], v141, s[76:77] offset:384
	global_load_dwordx2 v[156:157], v141, s[76:77] offset:1024
	global_load_dwordx2 v[162:163], v141, s[76:77] offset:1152
	global_load_dwordx2 v[164:165], v141, s[76:77] offset:1280
	global_load_dwordx2 v[166:167], v141, s[76:77] offset:1408
	global_load_dwordx4 v[168:171], v144, s[72:73]
	global_load_dwordx4 v[172:175], v144, s[74:75]
	global_load_dwordx4 v[176:179], v144, s[72:73] offset:64
	global_load_dwordx4 v[186:189], v144, s[74:75] offset:64
	global_load_dwordx4 v[190:193], v140, s[78:79]
	global_load_dwordx4 v[194:197], v140, s[80:81]
	global_load_dwordx4 v[198:201], v140, s[82:83]
	global_load_dwordx4 v[204:207], v140, s[84:85]
	global_load_dwordx4 v[208:211], v140, s[86:87]
	global_load_dwordx4 v[212:215], v140, s[88:89]
	global_load_dwordx4 v[216:219], v140, s[90:91]
	global_load_dwordx4 v[220:223], v140, s[92:93]
	global_load_dwordx4 v[224:227], v140, s[78:79] offset:64
	global_load_dwordx4 v[228:231], v140, s[80:81] offset:64
	global_load_dwordx4 v[232:235], v140, s[82:83] offset:64
	global_load_dwordx4 v[236:239], v140, s[84:85] offset:64
	global_load_dwordx4 v[240:243], v140, s[86:87] offset:64
	global_load_dwordx4 v[244:247], v140, s[88:89] offset:64
	s_waitcnt vmcnt(13)
; DI bf16x4 pack4(float a, float b, float c, float d) { u32x2v u; u.x = pk2(a, b); u.y = pk2(c, d); return __builtin_bit_cast(bf16x4, u); }
;   DI void operator()(const f32x4 (&acc)[2][2][4][2], const pg8::Unit& u, int wr, int wc, int fr, int fq) const {
;     ...
;           for (int n = 0; n < 2; ++n) {
;             const size_t idx = (size_t)row * 1024 + u.pn * 256 + 128 * bj + 32 * wc + 16 * n + 4 * fq;
;             const f32x4 a = acc[ai][bj][m][n];
;             if (MODE == 0) {
;               const unsigned g = *reinterpret_cast<const unsigned*>(reinterpret_cast<const unsigned char*>(p.ws + OFF_RB) + idx);
;               const float k = 1.f / 255.f;
;               st4(MERGED + idx, pack4((float)(g & 255u) * k * a[0], (float)((g >> 8) & 255u) * k * a[1], (float)((g >> 16) & 255u) * k * a[2], (float)(g >> 24) * k * a[3]));
;             } else {
;               f32x4 x = *reinterpret_cast<const f32x4*>(p.out + idx);
;               x = x * ALPHA + a;
;               *reinterpret_cast<f32x4*>(p.out + idx) = x;
;             }
	v_pk_add_f32 v[190:191], v[190:191], v[146:147] op_sel_hi:[1,0] neg_lo:[0,1] neg_hi:[0,1]
	v_pk_add_f32 v[192:193], v[192:193], v[146:147] op_sel_hi:[1,0] neg_lo:[0,1] neg_hi:[0,1]
	v_pk_mul_f32 v[190:191], v[190:191], v[146:147] op_sel:[0,1] op_sel_hi:[1,1]
	v_pk_mul_f32 v[192:193], v[192:193], v[146:147] op_sel:[0,1] op_sel_hi:[1,1]
	v_pk_fma_f32 v[190:191], v[190:191], v[168:169], v[172:173]
	v_pk_fma_f32 v[192:193], v[192:193], v[170:171], v[174:175]
	v_pk_fma_f32 v[130:131], v[190:191], s[16:17], v[130:131] op_sel_hi:[1,0,1]
	v_pk_fma_f32 v[132:133], v[192:193], s[16:17], v[132:133] op_sel_hi:[1,0,1]
	global_store_dwordx4 v140, v[130:133], s[56:57]
	global_load_dwordx4 v[190:193], v140, s[90:91] offset:64
	s_waitcnt vmcnt(14)
	v_pk_add_f32 v[194:195], v[194:195], v[148:149] op_sel_hi:[1,0] neg_lo:[0,1] neg_hi:[0,1]
	v_pk_add_f32 v[196:197], v[196:197], v[148:149] op_sel_hi:[1,0] neg_lo:[0,1] neg_hi:[0,1]
	v_pk_mul_f32 v[194:195], v[194:195], v[148:149] op_sel:[0,1] op_sel_hi:[1,1]
	v_pk_mul_f32 v[196:197], v[196:197], v[148:149] op_sel:[0,1] op_sel_hi:[1,1]
	v_pk_fma_f32 v[194:195], v[194:195], v[168:169], v[172:173]
	v_pk_fma_f32 v[196:197], v[196:197], v[170:171], v[174:175]
	v_pk_fma_f32 v[114:115], v[194:195], s[16:17], v[114:115] op_sel_hi:[1,0,1]
	v_pk_fma_f32 v[116:117], v[196:197], s[16:17], v[116:117] op_sel_hi:[1,0,1]
	global_store_dwordx4 v140, v[114:117], s[58:59]
	global_load_dwordx4 v[194:197], v140, s[92:93] offset:64
	s_waitcnt vmcnt(15)
	v_pk_add_f32 v[198:199], v[198:199], v[150:151] op_sel_hi:[1,0] neg_lo:[0,1] neg_hi:[0,1]
	v_pk_add_f32 v[200:201], v[200:201], v[150:151] op_sel_hi:[1,0] neg_lo:[0,1] neg_hi:[0,1]
	v_pk_mul_f32 v[198:199], v[198:199], v[150:151] op_sel:[0,1] op_sel_hi:[1,1]
	v_pk_mul_f32 v[200:201], v[200:201], v[150:151] op_sel:[0,1] op_sel_hi:[1,1]
	v_pk_fma_f32 v[198:199], v[198:199], v[168:169], v[172:173]
	v_pk_fma_f32 v[200:201], v[200:201], v[170:171], v[174:175]
	v_pk_fma_f32 v[98:99], v[198:199], s[16:17], v[98:99] op_sel_hi:[1,0,1]
	v_pk_fma_f32 v[100:101], v[200:201], s[16:17], v[100:101] op_sel_hi:[1,0,1]
	global_store_dwordx4 v140, v[98:101], s[60:61]
	global_load_dwordx4 v[198:201], v140, s[78:79] offset:512
	s_waitcnt vmcnt(16)
	v_pk_add_f32 v[204:205], v[204:205], v[154:155] op_sel_hi:[1,0] neg_lo:[0,1] neg_hi:[0,1]
	v_pk_add_f32 v[206:207], v[206:207], v[154:155] op_sel_hi:[1,0] neg_lo:[0,1] neg_hi:[0,1]
	v_pk_mul_f32 v[204:205], v[204:205], v[154:155] op_sel:[0,1] op_sel_hi:[1,1]
	v_pk_mul_f32 v[206:207], v[206:207], v[154:155] op_sel:[0,1] op_sel_hi:[1,1]
	v_pk_fma_f32 v[204:205], v[204:205], v[168:169], v[172:173]
	v_pk_fma_f32 v[206:207], v[206:207], v[170:171], v[174:175]
	v_pk_fma_f32 v[82:83], v[204:205], s[16:17], v[82:83] op_sel_hi:[1,0,1]
	v_pk_fma_f32 v[84:85], v[206:207], s[16:17], v[84:85] op_sel_hi:[1,0,1]
	global_store_dwordx4 v140, v[82:85], s[62:63]
	global_load_dwordx4 v[204:207], v140, s[80:81] offset:512
	s_waitcnt vmcnt(17)
	v_pk_add_f32 v[208:209], v[208:209], v[156:157] op_sel_hi:[1,0] neg_lo:[0,1] neg_hi:[0,1]
	v_pk_add_f32 v[210:211], v[210:211], v[156:157] op_sel_hi:[1,0] neg_lo:[0,1] neg_hi:[0,1]
	v_pk_mul_f32 v[208:209], v[208:209], v[156:157] op_sel:[0,1] op_sel_hi:[1,1]
	v_pk_mul_f32 v[210:211], v[210:211], v[156:157] op_sel:[0,1] op_sel_hi:[1,1]
	v_pk_fma_f32 v[208:209], v[208:209], v[168:169], v[172:173]
	v_pk_fma_f32 v[210:211], v[210:211], v[170:171], v[174:175]
	v_pk_fma_f32 v[66:67], v[208:209], s[16:17], v[66:67] op_sel_hi:[1,0,1]
	v_pk_fma_f32 v[68:69], v[210:211], s[16:17], v[68:69] op_sel_hi:[1,0,1]
	global_store_dwordx4 v140, v[66:69], s[64:65]
	global_load_dwordx4 v[208:211], v140, s[82:83] offset:512
	s_waitcnt vmcnt(18)
	v_pk_add_f32 v[212:213], v[212:213], v[162:163] op_sel_hi:[1,0] neg_lo:[0,1] neg_hi:[0,1]
	v_pk_add_f32 v[214:215], v[214:215], v[162:163] op_sel_hi:[1,0] neg_lo:[0,1] neg_hi:[0,1]
	v_pk_mul_f32 v[212:213], v[212:213], v[162:163] op_sel:[0,1] op_sel_hi:[1,1]
	v_pk_mul_f32 v[214:215], v[214:215], v[162:163] op_sel:[0,1] op_sel_hi:[1,1]
	v_pk_fma_f32 v[212:213], v[212:213], v[168:169], v[172:173]
	v_pk_fma_f32 v[214:215], v[214:215], v[170:171], v[174:175]
	v_pk_fma_f32 v[50:51], v[212:213], s[16:17], v[50:51] op_sel_hi:[1,0,1]
	v_pk_fma_f32 v[52:53], v[214:215], s[16:17], v[52:53] op_sel_hi:[1,0,1]
	global_store_dwordx4 v140, v[50:53], s[66:67]
	global_load_dwordx4 v[212:215], v140, s[84:85] offset:512
	s_waitcnt vmcnt(19)
	v_pk_add_f32 v[216:217], v[216:217], v[164:165] op_sel_hi:[1,0] neg_lo:[0,1] neg_hi:[0,1]
	v_pk_add_f32 v[218:219], v[218:219], v[164:165] op_sel_hi:[1,0] neg_lo:[0,1] neg_hi:[0,1]
	v_pk_mul_f32 v[216:217], v[216:217], v[164:165] op_sel:[0,1] op_sel_hi:[1,1]
	v_pk_mul_f32 v[218:219], v[218:219], v[164:165] op_sel:[0,1] op_sel_hi:[1,1]
	v_pk_fma_f32 v[216:217], v[216:217], v[168:169], v[172:173]
	v_pk_fma_f32 v[218:219], v[218:219], v[170:171], v[174:175]
	v_pk_fma_f32 v[34:35], v[216:217], s[16:17], v[34:35] op_sel_hi:[1,0,1]
	v_pk_fma_f32 v[36:37], v[218:219], s[16:17], v[36:37] op_sel_hi:[1,0,1]
	global_store_dwordx4 v140, v[34:37], s[68:69]
	global_load_dwordx4 v[216:219], v140, s[86:87] offset:512
	s_waitcnt vmcnt(20)
	v_pk_add_f32 v[220:221], v[220:221], v[166:167] op_sel_hi:[1,0] neg_lo:[0,1] neg_hi:[0,1]
	v_pk_add_f32 v[222:223], v[222:223], v[166:167] op_sel_hi:[1,0] neg_lo:[0,1] neg_hi:[0,1]
	v_pk_mul_f32 v[220:221], v[220:221], v[166:167] op_sel:[0,1] op_sel_hi:[1,1]
	v_pk_mul_f32 v[222:223], v[222:223], v[166:167] op_sel:[0,1] op_sel_hi:[1,1]
	v_pk_fma_f32 v[220:221], v[220:221], v[168:169], v[172:173]
	v_pk_fma_f32 v[222:223], v[222:223], v[170:171], v[174:175]
	v_pk_fma_f32 v[12:13], v[220:221], s[16:17], v[12:13] op_sel_hi:[1,0,1]
	v_pk_fma_f32 v[14:15], v[222:223], s[16:17], v[14:15] op_sel_hi:[1,0,1]
	global_store_dwordx4 v140, v[12:15], s[70:71]
	global_load_dwordx4 v[220:223], v140, s[88:89] offset:512
	global_load_dwordx4 v[168:171], v144, s[72:73] offset:512
	global_load_dwordx4 v[172:175], v144, s[74:75] offset:512
	s_waitcnt vmcnt(23)
; DI bf16x4 pack4(float a, float b, float c, float d) { u32x2v u; u.x = pk2(a, b); u.y = pk2(c, d); return __builtin_bit_cast(bf16x4, u); }
;   DI void operator()(const f32x4 (&acc)[2][2][4][2], const pg8::Unit& u, int wr, int wc, int fr, int fq) const {
;     ...
;           for (int n = 0; n < 2; ++n) {
;             const size_t idx = (size_t)row * 1024 + u.pn * 256 + 128 * bj + 32 * wc + 16 * n + 4 * fq;
;             const f32x4 a = acc[ai][bj][m][n];
;             if (MODE == 0) {
;               const unsigned g = *reinterpret_cast<const unsigned*>(reinterpret_cast<const unsigned char*>(p.ws + OFF_RB) + idx);
;               const float k = 1.f / 255.f;
;               st4(MERGED + idx, pack4((float)(g & 255u) * k * a[0], (float)((g >> 8) & 255u) * k * a[1], (float)((g >> 16) & 255u) * k * a[2], (float)(g >> 24) * k * a[3]));
;             } else {
;               f32x4 x = *reinterpret_cast<const f32x4*>(p.out + idx);
;               x = x * ALPHA + a;
;               *reinterpret_cast<f32x4*>(p.out + idx) = x;
;             }
	v_pk_add_f32 v[224:225], v[224:225], v[146:147] op_sel_hi:[1,0] neg_lo:[0,1] neg_hi:[0,1]
	v_pk_add_f32 v[226:227], v[226:227], v[146:147] op_sel_hi:[1,0] neg_lo:[0,1] neg_hi:[0,1]
	v_pk_mul_f32 v[224:225], v[224:225], v[146:147] op_sel:[0,1] op_sel_hi:[1,1]
	v_pk_mul_f32 v[226:227], v[226:227], v[146:147] op_sel:[0,1] op_sel_hi:[1,1]
	v_pk_fma_f32 v[224:225], v[224:225], v[176:177], v[186:187]
	v_pk_fma_f32 v[226:227], v[226:227], v[178:179], v[188:189]
	v_pk_fma_f32 v[126:127], v[224:225], s[16:17], v[126:127] op_sel_hi:[1,0,1]
	v_pk_fma_f32 v[128:129], v[226:227], s[16:17], v[128:129] op_sel_hi:[1,0,1]
	global_store_dwordx4 v140, v[126:129], s[56:57] offset:64
	global_load_dwordx4 v[224:227], v140, s[90:91] offset:512
	s_waitcnt vmcnt(24)
	v_pk_add_f32 v[228:229], v[228:229], v[148:149] op_sel_hi:[1,0] neg_lo:[0,1] neg_hi:[0,1]
	v_pk_add_f32 v[230:231], v[230:231], v[148:149] op_sel_hi:[1,0] neg_lo:[0,1] neg_hi:[0,1]
	v_pk_mul_f32 v[228:229], v[228:229], v[148:149] op_sel:[0,1] op_sel_hi:[1,1]
	v_pk_mul_f32 v[230:231], v[230:231], v[148:149] op_sel:[0,1] op_sel_hi:[1,1]
	v_pk_fma_f32 v[228:229], v[228:229], v[176:177], v[186:187]
	v_pk_fma_f32 v[230:231], v[230:231], v[178:179], v[188:189]
	v_pk_fma_f32 v[110:111], v[228:229], s[16:17], v[110:111] op_sel_hi:[1,0,1]
	v_pk_fma_f32 v[112:113], v[230:231], s[16:17], v[112:113] op_sel_hi:[1,0,1]
	global_store_dwordx4 v140, v[110:113], s[58:59] offset:64
	global_load_dwordx4 v[228:231], v140, s[92:93] offset:512
	s_waitcnt vmcnt(25)
	v_pk_add_f32 v[232:233], v[232:233], v[150:151] op_sel_hi:[1,0] neg_lo:[0,1] neg_hi:[0,1]
	v_pk_add_f32 v[234:235], v[234:235], v[150:151] op_sel_hi:[1,0] neg_lo:[0,1] neg_hi:[0,1]
	v_pk_mul_f32 v[232:233], v[232:233], v[150:151] op_sel:[0,1] op_sel_hi:[1,1]
	v_pk_mul_f32 v[234:235], v[234:235], v[150:151] op_sel:[0,1] op_sel_hi:[1,1]
	v_pk_fma_f32 v[232:233], v[232:233], v[176:177], v[186:187]
	v_pk_fma_f32 v[234:235], v[234:235], v[178:179], v[188:189]
	v_pk_fma_f32 v[94:95], v[232:233], s[16:17], v[94:95] op_sel_hi:[1,0,1]
	v_pk_fma_f32 v[96:97], v[234:235], s[16:17], v[96:97] op_sel_hi:[1,0,1]
	global_store_dwordx4 v140, v[94:97], s[60:61] offset:64
	global_load_dwordx4 v[232:235], v140, s[78:79] offset:576
	s_waitcnt vmcnt(26)
	v_pk_add_f32 v[236:237], v[236:237], v[154:155] op_sel_hi:[1,0] neg_lo:[0,1] neg_hi:[0,1]
	v_pk_add_f32 v[238:239], v[238:239], v[154:155] op_sel_hi:[1,0] neg_lo:[0,1] neg_hi:[0,1]
	v_pk_mul_f32 v[236:237], v[236:237], v[154:155] op_sel:[0,1] op_sel_hi:[1,1]
	v_pk_mul_f32 v[238:239], v[238:239], v[154:155] op_sel:[0,1] op_sel_hi:[1,1]
	v_pk_fma_f32 v[236:237], v[236:237], v[176:177], v[186:187]
	v_pk_fma_f32 v[238:239], v[238:239], v[178:179], v[188:189]
	v_pk_fma_f32 v[78:79], v[236:237], s[16:17], v[78:79] op_sel_hi:[1,0,1]
	v_pk_fma_f32 v[80:81], v[238:239], s[16:17], v[80:81] op_sel_hi:[1,0,1]
	global_store_dwordx4 v140, v[78:81], s[62:63] offset:64
	global_load_dwordx4 v[236:239], v140, s[80:81] offset:576
	s_waitcnt vmcnt(27)
	v_pk_add_f32 v[240:241], v[240:241], v[156:157] op_sel_hi:[1,0] neg_lo:[0,1] neg_hi:[0,1]
	v_pk_add_f32 v[242:243], v[242:243], v[156:157] op_sel_hi:[1,0] neg_lo:[0,1] neg_hi:[0,1]
	v_pk_mul_f32 v[240:241], v[240:241], v[156:157] op_sel:[0,1] op_sel_hi:[1,1]
	v_pk_mul_f32 v[242:243], v[242:243], v[156:157] op_sel:[0,1] op_sel_hi:[1,1]
	v_pk_fma_f32 v[240:241], v[240:241], v[176:177], v[186:187]
	v_pk_fma_f32 v[242:243], v[242:243], v[178:179], v[188:189]
	v_pk_fma_f32 v[62:63], v[240:241], s[16:17], v[62:63] op_sel_hi:[1,0,1]
	v_pk_fma_f32 v[64:65], v[242:243], s[16:17], v[64:65] op_sel_hi:[1,0,1]
	global_store_dwordx4 v140, v[62:65], s[64:65] offset:64
	global_load_dwordx4 v[240:243], v140, s[82:83] offset:576
	s_waitcnt vmcnt(28)
	v_pk_add_f32 v[244:245], v[244:245], v[162:163] op_sel_hi:[1,0] neg_lo:[0,1] neg_hi:[0,1]
	v_pk_add_f32 v[246:247], v[246:247], v[162:163] op_sel_hi:[1,0] neg_lo:[0,1] neg_hi:[0,1]
	v_pk_mul_f32 v[244:245], v[244:245], v[162:163] op_sel:[0,1] op_sel_hi:[1,1]
	v_pk_mul_f32 v[246:247], v[246:247], v[162:163] op_sel:[0,1] op_sel_hi:[1,1]
	v_pk_fma_f32 v[244:245], v[244:245], v[176:177], v[186:187]
	v_pk_fma_f32 v[246:247], v[246:247], v[178:179], v[188:189]
	v_pk_fma_f32 v[46:47], v[244:245], s[16:17], v[46:47] op_sel_hi:[1,0,1]
	v_pk_fma_f32 v[48:49], v[246:247], s[16:17], v[48:49] op_sel_hi:[1,0,1]
	global_store_dwordx4 v140, v[46:49], s[66:67] offset:64
	global_load_dwordx4 v[244:247], v140, s[84:85] offset:576
	s_waitcnt vmcnt(28)
	v_pk_add_f32 v[190:191], v[190:191], v[164:165] op_sel_hi:[1,0] neg_lo:[0,1] neg_hi:[0,1]
	v_pk_add_f32 v[192:193], v[192:193], v[164:165] op_sel_hi:[1,0] neg_lo:[0,1] neg_hi:[0,1]
	v_pk_mul_f32 v[190:191], v[190:191], v[164:165] op_sel:[0,1] op_sel_hi:[1,1]
	v_pk_mul_f32 v[192:193], v[192:193], v[164:165] op_sel:[0,1] op_sel_hi:[1,1]
	v_pk_fma_f32 v[190:191], v[190:191], v[176:177], v[186:187]
	v_pk_fma_f32 v[192:193], v[192:193], v[178:179], v[188:189]
	v_pk_fma_f32 v[30:31], v[190:191], s[16:17], v[30:31] op_sel_hi:[1,0,1]
	v_pk_fma_f32 v[32:33], v[192:193], s[16:17], v[32:33] op_sel_hi:[1,0,1]
	global_store_dwordx4 v140, v[30:33], s[68:69] offset:64
	global_load_dwordx4 v[190:193], v140, s[86:87] offset:576
	s_waitcnt vmcnt(28)
; DI bf16x4 pack4(float a, float b, float c, float d) { u32x2v u; u.x = pk2(a, b); u.y = pk2(c, d); return __builtin_bit_cast(bf16x4, u); }
;   DI void operator()(const f32x4 (&acc)[2][2][4][2], const pg8::Unit& u, int wr, int wc, int fr, int fq) const {
;     ...
;           for (int n = 0; n < 2; ++n) {
;             const size_t idx = (size_t)row * 1024 + u.pn * 256 + 128 * bj + 32 * wc + 16 * n + 4 * fq;
;             const f32x4 a = acc[ai][bj][m][n];
;             if (MODE == 0) {
;               const unsigned g = *reinterpret_cast<const unsigned*>(reinterpret_cast<const unsigned char*>(p.ws + OFF_RB) + idx);
;               const float k = 1.f / 255.f;
;               st4(MERGED + idx, pack4((float)(g & 255u) * k * a[0], (float)((g >> 8) & 255u) * k * a[1], (float)((g >> 16) & 255u) * k * a[2], (float)(g >> 24) * k * a[3]));
;             } else {
;               f32x4 x = *reinterpret_cast<const f32x4*>(p.out + idx);
;               x = x * ALPHA + a;
;               *reinterpret_cast<f32x4*>(p.out + idx) = x;
;             }
	v_pk_add_f32 v[194:195], v[194:195], v[166:167] op_sel_hi:[1,0] neg_lo:[0,1] neg_hi:[0,1]
	v_pk_add_f32 v[196:197], v[196:197], v[166:167] op_sel_hi:[1,0] neg_lo:[0,1] neg_hi:[0,1]
	v_pk_mul_f32 v[194:195], v[194:195], v[166:167] op_sel:[0,1] op_sel_hi:[1,1]
	v_pk_mul_f32 v[196:197], v[196:197], v[166:167] op_sel:[0,1] op_sel_hi:[1,1]
	v_pk_fma_f32 v[194:195], v[194:195], v[176:177], v[186:187]
	v_pk_fma_f32 v[196:197], v[196:197], v[178:179], v[188:189]
	v_pk_fma_f32 v[8:9], v[194:195], s[16:17], v[8:9] op_sel_hi:[1,0,1]
	v_pk_fma_f32 v[10:11], v[196:197], s[16:17], v[10:11] op_sel_hi:[1,0,1]
	global_store_dwordx4 v140, v[8:11], s[70:71] offset:64
	global_load_dwordx4 v[194:197], v140, s[88:89] offset:576
	global_load_dwordx4 v[176:179], v144, s[72:73] offset:576
	global_load_dwordx4 v[186:189], v144, s[74:75] offset:576
	s_waitcnt vmcnt(18)
	v_pk_add_f32 v[198:199], v[198:199], v[146:147] op_sel_hi:[1,0] neg_lo:[0,1] neg_hi:[0,1]
	v_pk_add_f32 v[200:201], v[200:201], v[146:147] op_sel_hi:[1,0] neg_lo:[0,1] neg_hi:[0,1]
	v_pk_mul_f32 v[198:199], v[198:199], v[146:147] op_sel:[0,1] op_sel_hi:[1,1]
	v_pk_mul_f32 v[200:201], v[200:201], v[146:147] op_sel:[0,1] op_sel_hi:[1,1]
	v_pk_fma_f32 v[198:199], v[198:199], v[168:169], v[172:173]
	v_pk_fma_f32 v[200:201], v[200:201], v[170:171], v[174:175]
	v_pk_fma_f32 v[122:123], v[198:199], s[16:17], v[122:123] op_sel_hi:[1,0,1]
	v_pk_fma_f32 v[124:125], v[200:201], s[16:17], v[124:125] op_sel_hi:[1,0,1]
	global_store_dwordx4 v140, v[122:125], s[56:57] offset:512
	global_load_dwordx4 v[198:201], v140, s[90:91] offset:576
	s_waitcnt vmcnt(20)
	v_pk_add_f32 v[204:205], v[204:205], v[148:149] op_sel_hi:[1,0] neg_lo:[0,1] neg_hi:[0,1]
	v_pk_add_f32 v[206:207], v[206:207], v[148:149] op_sel_hi:[1,0] neg_lo:[0,1] neg_hi:[0,1]
	v_pk_mul_f32 v[204:205], v[204:205], v[148:149] op_sel:[0,1] op_sel_hi:[1,1]
	v_pk_mul_f32 v[206:207], v[206:207], v[148:149] op_sel:[0,1] op_sel_hi:[1,1]
	v_pk_fma_f32 v[204:205], v[204:205], v[168:169], v[172:173]
	v_pk_fma_f32 v[206:207], v[206:207], v[170:171], v[174:175]
	v_pk_fma_f32 v[106:107], v[204:205], s[16:17], v[106:107] op_sel_hi:[1,0,1]
	v_pk_fma_f32 v[108:109], v[206:207], s[16:17], v[108:109] op_sel_hi:[1,0,1]
	global_store_dwordx4 v140, v[106:109], s[58:59] offset:512
	global_load_dwordx4 v[204:207], v140, s[92:93] offset:576
	s_waitcnt vmcnt(22)
	v_pk_add_f32 v[208:209], v[208:209], v[150:151] op_sel_hi:[1,0] neg_lo:[0,1] neg_hi:[0,1]
	v_pk_add_f32 v[210:211], v[210:211], v[150:151] op_sel_hi:[1,0] neg_lo:[0,1] neg_hi:[0,1]
	v_pk_mul_f32 v[208:209], v[208:209], v[150:151] op_sel:[0,1] op_sel_hi:[1,1]
	v_pk_mul_f32 v[210:211], v[210:211], v[150:151] op_sel:[0,1] op_sel_hi:[1,1]
	v_pk_fma_f32 v[208:209], v[208:209], v[168:169], v[172:173]
	v_pk_fma_f32 v[210:211], v[210:211], v[170:171], v[174:175]
	v_pk_fma_f32 v[90:91], v[208:209], s[16:17], v[90:91] op_sel_hi:[1,0,1]
	v_pk_fma_f32 v[92:93], v[210:211], s[16:17], v[92:93] op_sel_hi:[1,0,1]
	global_store_dwordx4 v140, v[90:93], s[60:61] offset:512
	s_waitcnt vmcnt(23)
	v_pk_add_f32 v[212:213], v[212:213], v[154:155] op_sel_hi:[1,0] neg_lo:[0,1] neg_hi:[0,1]
	v_pk_add_f32 v[214:215], v[214:215], v[154:155] op_sel_hi:[1,0] neg_lo:[0,1] neg_hi:[0,1]
	v_pk_mul_f32 v[212:213], v[212:213], v[154:155] op_sel:[0,1] op_sel_hi:[1,1]
	v_pk_mul_f32 v[214:215], v[214:215], v[154:155] op_sel:[0,1] op_sel_hi:[1,1]
	v_pk_fma_f32 v[212:213], v[212:213], v[168:169], v[172:173]
	v_pk_fma_f32 v[214:215], v[214:215], v[170:171], v[174:175]
	v_pk_fma_f32 v[74:75], v[212:213], s[16:17], v[74:75] op_sel_hi:[1,0,1]
	v_pk_fma_f32 v[76:77], v[214:215], s[16:17], v[76:77] op_sel_hi:[1,0,1]
	global_store_dwordx4 v140, v[74:77], s[62:63] offset:512
	s_waitcnt vmcnt(24)
	v_pk_add_f32 v[216:217], v[216:217], v[156:157] op_sel_hi:[1,0] neg_lo:[0,1] neg_hi:[0,1]
	v_pk_add_f32 v[218:219], v[218:219], v[156:157] op_sel_hi:[1,0] neg_lo:[0,1] neg_hi:[0,1]
	v_pk_mul_f32 v[216:217], v[216:217], v[156:157] op_sel:[0,1] op_sel_hi:[1,1]
	v_pk_mul_f32 v[218:219], v[218:219], v[156:157] op_sel:[0,1] op_sel_hi:[1,1]
	v_pk_fma_f32 v[216:217], v[216:217], v[168:169], v[172:173]
	v_pk_fma_f32 v[218:219], v[218:219], v[170:171], v[174:175]
	v_pk_fma_f32 v[58:59], v[216:217], s[16:17], v[58:59] op_sel_hi:[1,0,1]
	v_pk_fma_f32 v[60:61], v[218:219], s[16:17], v[60:61] op_sel_hi:[1,0,1]
	global_store_dwordx4 v140, v[58:61], s[64:65] offset:512
	s_waitcnt vmcnt(25)
	v_pk_add_f32 v[220:221], v[220:221], v[162:163] op_sel_hi:[1,0] neg_lo:[0,1] neg_hi:[0,1]
	v_pk_add_f32 v[222:223], v[222:223], v[162:163] op_sel_hi:[1,0] neg_lo:[0,1] neg_hi:[0,1]
	v_pk_mul_f32 v[220:221], v[220:221], v[162:163] op_sel:[0,1] op_sel_hi:[1,1]
	v_pk_mul_f32 v[222:223], v[222:223], v[162:163] op_sel:[0,1] op_sel_hi:[1,1]
	v_pk_fma_f32 v[220:221], v[220:221], v[168:169], v[172:173]
	v_pk_fma_f32 v[222:223], v[222:223], v[170:171], v[174:175]
	v_pk_fma_f32 v[42:43], v[220:221], s[16:17], v[42:43] op_sel_hi:[1,0,1]
	v_pk_fma_f32 v[44:45], v[222:223], s[16:17], v[44:45] op_sel_hi:[1,0,1]
	global_store_dwordx4 v140, v[42:45], s[66:67] offset:512
	s_waitcnt vmcnt(24)
	v_pk_add_f32 v[224:225], v[224:225], v[164:165] op_sel_hi:[1,0] neg_lo:[0,1] neg_hi:[0,1]
	v_pk_add_f32 v[226:227], v[226:227], v[164:165] op_sel_hi:[1,0] neg_lo:[0,1] neg_hi:[0,1]
	v_pk_mul_f32 v[224:225], v[224:225], v[164:165] op_sel:[0,1] op_sel_hi:[1,1]
	v_pk_mul_f32 v[226:227], v[226:227], v[164:165] op_sel:[0,1] op_sel_hi:[1,1]
	v_pk_fma_f32 v[224:225], v[224:225], v[168:169], v[172:173]
	v_pk_fma_f32 v[226:227], v[226:227], v[170:171], v[174:175]
	v_pk_fma_f32 v[26:27], v[224:225], s[16:17], v[26:27] op_sel_hi:[1,0,1]
	v_pk_fma_f32 v[28:29], v[226:227], s[16:17], v[28:29] op_sel_hi:[1,0,1]
	global_store_dwordx4 v140, v[26:29], s[68:69] offset:512
	s_waitcnt vmcnt(23)
; DI bf16x4 pack4(float a, float b, float c, float d) { u32x2v u; u.x = pk2(a, b); u.y = pk2(c, d); return __builtin_bit_cast(bf16x4, u); }
; template <class Epi, class Sched>
; __device__ __forceinline__ void gemm_phase(PG8_LAS unsigned char* lds, const Gemm g, const Sched& S, const Epi& E) {
;     ...
;         if constexpr (!Epi::AFTER_DRAIN) { E(acc, cur, wr, wc, fr, fq); S.done(cur); }
;         if (!has_next) break;
; #pragma unroll
;         for (int a = 0; a < 2; ++a)
; #pragma unroll
;             for (int b = 0; b < 2; ++b)
; #pragma unroll
;                 for (int m = 0; m < 4; ++m)
; #pragma unroll
;                     for (int n = 0; n < 2; ++n) acc[a][b][m][n] = (f32x4){0.f, 0.f, 0.f, 0.f};
;         cur = nxt; cA = nA; cB = nB; ++ui;
;   DI void operator()(const f32x4 (&acc)[2][2][4][2], const pg8::Unit& u, int wr, int wc, int fr, int fq) const {
;     ...
;           for (int n = 0; n < 2; ++n) {
;             const size_t idx = (size_t)row * 1024 + u.pn * 256 + 128 * bj + 32 * wc + 16 * n + 4 * fq;
;             const f32x4 a = acc[ai][bj][m][n];
;             if (MODE == 0) {
;               const unsigned g = *reinterpret_cast<const unsigned*>(reinterpret_cast<const unsigned char*>(p.ws + OFF_RB) + idx);
;               const float k = 1.f / 255.f;
;               st4(MERGED + idx, pack4((float)(g & 255u) * k * a[0], (float)((g >> 8) & 255u) * k * a[1], (float)((g >> 16) & 255u) * k * a[2], (float)(g >> 24) * k * a[3]));
;             } else {
;               f32x4 x = *reinterpret_cast<const f32x4*>(p.out + idx);
;               x = x * ALPHA + a;
;               *reinterpret_cast<f32x4*>(p.out + idx) = x;
;             }
	v_pk_add_f32 v[228:229], v[228:229], v[166:167] op_sel_hi:[1,0] neg_lo:[0,1] neg_hi:[0,1]
	v_pk_add_f32 v[230:231], v[230:231], v[166:167] op_sel_hi:[1,0] neg_lo:[0,1] neg_hi:[0,1]
	v_pk_mul_f32 v[228:229], v[228:229], v[166:167] op_sel:[0,1] op_sel_hi:[1,1]
	v_pk_mul_f32 v[230:231], v[230:231], v[166:167] op_sel:[0,1] op_sel_hi:[1,1]
	v_pk_fma_f32 v[228:229], v[228:229], v[168:169], v[172:173]
	v_pk_fma_f32 v[230:231], v[230:231], v[170:171], v[174:175]
	v_pk_fma_f32 v[4:5], v[228:229], s[16:17], v[4:5] op_sel_hi:[1,0,1]
	v_pk_fma_f32 v[6:7], v[230:231], s[16:17], v[6:7] op_sel_hi:[1,0,1]
	global_store_dwordx4 v140, v[4:7], s[70:71] offset:512
	s_waitcnt vmcnt(10)
	v_pk_add_f32 v[232:233], v[232:233], v[146:147] op_sel_hi:[1,0] neg_lo:[0,1] neg_hi:[0,1]
	v_pk_add_f32 v[234:235], v[234:235], v[146:147] op_sel_hi:[1,0] neg_lo:[0,1] neg_hi:[0,1]
	v_pk_mul_f32 v[232:233], v[232:233], v[146:147] op_sel:[0,1] op_sel_hi:[1,1]
	v_pk_mul_f32 v[234:235], v[234:235], v[146:147] op_sel:[0,1] op_sel_hi:[1,1]
	v_pk_fma_f32 v[232:233], v[232:233], v[176:177], v[186:187]
	v_pk_fma_f32 v[234:235], v[234:235], v[178:179], v[188:189]
	v_pk_fma_f32 v[118:119], v[232:233], s[16:17], v[118:119] op_sel_hi:[1,0,1]
	v_pk_fma_f32 v[120:121], v[234:235], s[16:17], v[120:121] op_sel_hi:[1,0,1]
	global_store_dwordx4 v140, v[118:121], s[56:57] offset:576
	s_waitcnt vmcnt(11)
	v_pk_add_f32 v[236:237], v[236:237], v[148:149] op_sel_hi:[1,0] neg_lo:[0,1] neg_hi:[0,1]
	v_pk_add_f32 v[238:239], v[238:239], v[148:149] op_sel_hi:[1,0] neg_lo:[0,1] neg_hi:[0,1]
	v_pk_mul_f32 v[236:237], v[236:237], v[148:149] op_sel:[0,1] op_sel_hi:[1,1]
	v_pk_mul_f32 v[238:239], v[238:239], v[148:149] op_sel:[0,1] op_sel_hi:[1,1]
	v_pk_fma_f32 v[236:237], v[236:237], v[176:177], v[186:187]
	v_pk_fma_f32 v[238:239], v[238:239], v[178:179], v[188:189]
	v_pk_fma_f32 v[102:103], v[236:237], s[16:17], v[102:103] op_sel_hi:[1,0,1]
	v_pk_fma_f32 v[104:105], v[238:239], s[16:17], v[104:105] op_sel_hi:[1,0,1]
	global_store_dwordx4 v140, v[102:105], s[58:59] offset:576
	s_waitcnt vmcnt(12)
	v_pk_add_f32 v[240:241], v[240:241], v[150:151] op_sel_hi:[1,0] neg_lo:[0,1] neg_hi:[0,1]
	v_pk_add_f32 v[242:243], v[242:243], v[150:151] op_sel_hi:[1,0] neg_lo:[0,1] neg_hi:[0,1]
	v_pk_mul_f32 v[240:241], v[240:241], v[150:151] op_sel:[0,1] op_sel_hi:[1,1]
	v_pk_mul_f32 v[242:243], v[242:243], v[150:151] op_sel:[0,1] op_sel_hi:[1,1]
	v_pk_fma_f32 v[240:241], v[240:241], v[176:177], v[186:187]
	v_pk_fma_f32 v[242:243], v[242:243], v[178:179], v[188:189]
	v_pk_fma_f32 v[86:87], v[240:241], s[16:17], v[86:87] op_sel_hi:[1,0,1]
	v_pk_fma_f32 v[88:89], v[242:243], s[16:17], v[88:89] op_sel_hi:[1,0,1]
	global_store_dwordx4 v140, v[86:89], s[60:61] offset:576
	s_waitcnt vmcnt(13)
	v_pk_add_f32 v[244:245], v[244:245], v[154:155] op_sel_hi:[1,0] neg_lo:[0,1] neg_hi:[0,1]
	v_pk_add_f32 v[246:247], v[246:247], v[154:155] op_sel_hi:[1,0] neg_lo:[0,1] neg_hi:[0,1]
	v_pk_mul_f32 v[244:245], v[244:245], v[154:155] op_sel:[0,1] op_sel_hi:[1,1]
	v_pk_mul_f32 v[246:247], v[246:247], v[154:155] op_sel:[0,1] op_sel_hi:[1,1]
	v_pk_fma_f32 v[244:245], v[244:245], v[176:177], v[186:187]
	v_pk_fma_f32 v[246:247], v[246:247], v[178:179], v[188:189]
	v_pk_fma_f32 v[70:71], v[244:245], s[16:17], v[70:71] op_sel_hi:[1,0,1]
	v_pk_fma_f32 v[72:73], v[246:247], s[16:17], v[72:73] op_sel_hi:[1,0,1]
	global_store_dwordx4 v140, v[70:73], s[62:63] offset:576
	s_waitcnt vmcnt(14)
	v_pk_add_f32 v[190:191], v[190:191], v[156:157] op_sel_hi:[1,0] neg_lo:[0,1] neg_hi:[0,1]
	v_pk_add_f32 v[192:193], v[192:193], v[156:157] op_sel_hi:[1,0] neg_lo:[0,1] neg_hi:[0,1]
	v_pk_mul_f32 v[190:191], v[190:191], v[156:157] op_sel:[0,1] op_sel_hi:[1,1]
	v_pk_mul_f32 v[192:193], v[192:193], v[156:157] op_sel:[0,1] op_sel_hi:[1,1]
	v_pk_fma_f32 v[190:191], v[190:191], v[176:177], v[186:187]
	v_pk_fma_f32 v[192:193], v[192:193], v[178:179], v[188:189]
	v_pk_fma_f32 v[54:55], v[190:191], s[16:17], v[54:55] op_sel_hi:[1,0,1]
	v_pk_fma_f32 v[56:57], v[192:193], s[16:17], v[56:57] op_sel_hi:[1,0,1]
	global_store_dwordx4 v140, v[54:57], s[64:65] offset:576
	s_waitcnt vmcnt(15)
	v_pk_add_f32 v[194:195], v[194:195], v[162:163] op_sel_hi:[1,0] neg_lo:[0,1] neg_hi:[0,1]
	v_pk_add_f32 v[196:197], v[196:197], v[162:163] op_sel_hi:[1,0] neg_lo:[0,1] neg_hi:[0,1]
	v_pk_mul_f32 v[194:195], v[194:195], v[162:163] op_sel:[0,1] op_sel_hi:[1,1]
	v_pk_mul_f32 v[196:197], v[196:197], v[162:163] op_sel:[0,1] op_sel_hi:[1,1]
	v_pk_fma_f32 v[194:195], v[194:195], v[176:177], v[186:187]
	v_pk_fma_f32 v[196:197], v[196:197], v[178:179], v[188:189]
	v_pk_fma_f32 v[38:39], v[194:195], s[16:17], v[38:39] op_sel_hi:[1,0,1]
	v_pk_fma_f32 v[40:41], v[196:197], s[16:17], v[40:41] op_sel_hi:[1,0,1]
	global_store_dwordx4 v140, v[38:41], s[66:67] offset:576
	s_waitcnt vmcnt(14)
	v_pk_add_f32 v[198:199], v[198:199], v[164:165] op_sel_hi:[1,0] neg_lo:[0,1] neg_hi:[0,1]
	v_pk_add_f32 v[200:201], v[200:201], v[164:165] op_sel_hi:[1,0] neg_lo:[0,1] neg_hi:[0,1]
	v_pk_mul_f32 v[198:199], v[198:199], v[164:165] op_sel:[0,1] op_sel_hi:[1,1]
	v_pk_mul_f32 v[200:201], v[200:201], v[164:165] op_sel:[0,1] op_sel_hi:[1,1]
	v_pk_fma_f32 v[198:199], v[198:199], v[176:177], v[186:187]
	v_pk_fma_f32 v[200:201], v[200:201], v[178:179], v[188:189]
	v_pk_fma_f32 v[22:23], v[198:199], s[16:17], v[22:23] op_sel_hi:[1,0,1]
	v_pk_fma_f32 v[24:25], v[200:201], s[16:17], v[24:25] op_sel_hi:[1,0,1]
	global_store_dwordx4 v140, v[22:25], s[68:69] offset:576
	s_waitcnt vmcnt(13)
	v_pk_add_f32 v[204:205], v[204:205], v[166:167] op_sel_hi:[1,0] neg_lo:[0,1] neg_hi:[0,1]
	v_pk_add_f32 v[206:207], v[206:207], v[166:167] op_sel_hi:[1,0] neg_lo:[0,1] neg_hi:[0,1]
	v_pk_mul_f32 v[204:205], v[204:205], v[166:167] op_sel:[0,1] op_sel_hi:[1,1]
	v_pk_mul_f32 v[206:207], v[206:207], v[166:167] op_sel:[0,1] op_sel_hi:[1,1]
	v_pk_fma_f32 v[204:205], v[204:205], v[176:177], v[186:187]
	v_pk_fma_f32 v[206:207], v[206:207], v[178:179], v[188:189]
	v_pk_fma_f32 v[0:1], v[204:205], s[16:17], v[0:1] op_sel_hi:[1,0,1]
	v_pk_fma_f32 v[2:3], v[206:207], s[16:17], v[2:3] op_sel_hi:[1,0,1]
	global_store_dwordx4 v140, v[0:3], s[70:71] offset:576
	s_mov_b32 s11, s2
	s_mov_b32 s10, s4
	s_mov_b64 s[14:15], s[8:9]
	s_mov_b64 s[12:13], s[6:7]
	s_and_b64 vcc, exec, s[0:1]
	s_cbranch_vccz .LBB0_2751
	s_waitcnt vmcnt(0)
	s_cmpk_gt_u32 s20, 0xff
	s_cbranch_scc1 .LBB0_2758
	s_barrier
